# v7 + GEMM2/3/5 epilogues: shfl_xor(16/32) cross-lane sums via v_permlane16/32_swap instead of ds_bpermute
# baseline (speedup 1.0000x reference)
.LBB0_507:
	s_lshl_b32 s37, s44, 8
	v_mbcnt_lo_u32_b32 v205, -1, 0
	v_mbcnt_hi_u32_b32 v205, -1, v205
	s_add_i32 s37, s37, s60
	v_ashrrev_i32_e32 v214, 3, v205
	v_add_u32_e32 v104, s37, v214
	v_ashrrev_i32_e32 v105, 31, v104
	s_lshl_b32 s44, s10, 8
	v_lshlrev_b64 v[104:105], 10, v[104:105]
	s_ashr_i32 s45, s44, 31
	v_lshl_add_u64 v[196:197], v[104:105], 0, s[44:45]
	v_or_b32_e32 v104, s66, v196
	v_lshlrev_b32_e32 v105, 3, v205
	v_and_or_b32 v196, v105, 56, v104
	v_lshl_add_u64 v[104:105], v[196:197], 1, s[16:17]
	v_add_co_u32_e32 v106, vcc, s58, v104
	v_mul_lo_u32 v214, v214, s68
	s_nop 0
	v_addc_co_u32_e32 v107, vcc, 0, v105, vcc
	global_load_dwordx4 v[206:209], v[104:105], off nt
	global_load_dwordx4 v[210:213], v[106:107], off nt
	v_add_co_u32_e32 v106, vcc, s64, v104
	v_lshlrev_b32_e32 v205, 4, v205
	s_nop 0
	v_addc_co_u32_e32 v107, vcc, 0, v105, vcc
	v_add_co_u32_e32 v108, vcc, s71, v104
	v_add_u32_e32 v214, s67, v214
	s_nop 0
	v_addc_co_u32_e32 v109, vcc, 0, v105, vcc
	global_load_dwordx4 v[176:179], v[106:107], off nt
	global_load_dwordx4 v[180:183], v[108:109], off nt
	v_add_co_u32_e32 v106, vcc, s56, v104
	v_and_b32_e32 v205, 0x70, v205
	s_nop 0
	v_addc_co_u32_e32 v107, vcc, 0, v105, vcc
	v_add_co_u32_e32 v108, vcc, s57, v104
	v_add_u32_e32 v205, v214, v205
	s_nop 0
	v_addc_co_u32_e32 v109, vcc, 0, v105, vcc
	global_load_dwordx4 v[168:171], v[106:107], off nt
	global_load_dwordx4 v[172:175], v[108:109], off nt
	v_add_co_u32_e32 v106, vcc, s63, v104
	s_lshl_b32 s44, s10, 2
	s_nop 0
	v_addc_co_u32_e32 v107, vcc, 0, v105, vcc
	v_add_co_u32_e32 v108, vcc, s65, v104
	s_ashr_i32 s45, s44, 31
	s_nop 0
	v_addc_co_u32_e32 v109, vcc, 0, v105, vcc
	global_load_dwordx4 v[160:163], v[106:107], off nt
	global_load_dwordx4 v[164:167], v[108:109], off nt
	v_add_co_u32_e32 v106, vcc, s72, v104
	s_nop 1
	v_addc_co_u32_e32 v107, vcc, 0, v105, vcc
	v_add_co_u32_e32 v108, vcc, s73, v104
	s_nop 1
	v_addc_co_u32_e32 v109, vcc, 0, v105, vcc
	global_load_dwordx4 v[152:155], v[106:107], off nt
	global_load_dwordx4 v[156:159], v[108:109], off nt
	v_add_co_u32_e32 v106, vcc, s74, v104
	s_nop 1
	v_addc_co_u32_e32 v107, vcc, 0, v105, vcc
	v_add_co_u32_e32 v108, vcc, s75, v104
	s_nop 1
	v_addc_co_u32_e32 v109, vcc, 0, v105, vcc
	global_load_dwordx4 v[144:147], v[106:107], off nt
	global_load_dwordx4 v[148:151], v[108:109], off nt
	v_add_co_u32_e32 v106, vcc, s79, v104
	s_nop 1
	v_addc_co_u32_e32 v107, vcc, 0, v105, vcc
	v_add_co_u32_e32 v108, vcc, s80, v104
	s_nop 1
	v_addc_co_u32_e32 v109, vcc, 0, v105, vcc
	global_load_dwordx4 v[124:127], v[106:107], off nt
	global_load_dwordx4 v[128:131], v[108:109], off nt
	v_add_co_u32_e32 v106, vcc, s81, v104
	s_nop 1
	v_addc_co_u32_e32 v107, vcc, 0, v105, vcc
	v_add_co_u32_e32 v108, vcc, s82, v104
	s_nop 1
	v_addc_co_u32_e32 v109, vcc, 0, v105, vcc
	global_load_dwordx4 v[104:107], v[106:107], off nt
	s_nop 0
	global_load_dwordx4 v[108:111], v[108:109], off nt
	s_waitcnt vmcnt(0)
	ds_write_b128 v205, v[206:209]
	ds_write_b128 v205, v[210:213] offset:1152
	ds_read_b128 v[206:209], v204
	ds_read_b128 v[210:213], v204 offset:64
	s_waitcnt lgkmcnt(1)
	v_lshlrev_b32_e32 v214, 16, v206
	v_and_b32_e32 v206, 0xffff0000, v206
	v_add_f32_e32 v206, v141, v206
	v_lshlrev_b32_e32 v141, 16, v207
	v_add_f32_e32 v141, v142, v141
	v_and_b32_e32 v142, 0xffff0000, v207
	v_add_f32_e32 v143, v143, v142
	v_lshlrev_b32_e32 v142, 16, v208
	v_add_f32_e32 v142, v136, v142
	v_and_b32_e32 v136, 0xffff0000, v208
	v_add_f32_e32 v207, v137, v136
	v_lshlrev_b32_e32 v136, 16, v209
	v_add_f32_e32 v138, v138, v136
	v_and_b32_e32 v136, 0xffff0000, v209
	v_add_f32_e32 v209, v139, v136
	s_waitcnt lgkmcnt(0)
	v_lshlrev_b32_e32 v136, 16, v210
	v_add_f32_e32 v136, v132, v136
	v_and_b32_e32 v132, 0xffff0000, v210
	v_add_f32_e32 v137, v133, v132
	v_lshlrev_b32_e32 v132, 16, v211
	v_add_f32_e32 v134, v134, v132
	v_and_b32_e32 v132, 0xffff0000, v211
	v_add_f32_e32 v139, v135, v132
	v_lshlrev_b32_e32 v132, 16, v212
	v_add_f32_e32 v135, v120, v132
	v_and_b32_e32 v120, 0xffff0000, v212
	v_add_f32_e32 v208, v121, v120
	v_lshlrev_b32_e32 v120, 16, v213
	v_add_f32_e32 v122, v122, v120
	v_and_b32_e32 v120, 0xffff0000, v213
	v_add_f32_e32 v140, v140, v214
	v_add_f32_e32 v123, v123, v120
	v_mul_f32_e32 v120, v206, v206
	v_mul_f32_e32 v121, v143, v143
	v_fmac_f32_e32 v120, v140, v140
	v_fmac_f32_e32 v121, v141, v141
	v_add_f32_e32 v120, v120, v121
	v_mul_f32_e32 v121, v207, v207
	v_mul_f32_e32 v132, v209, v209
	v_fmac_f32_e32 v121, v142, v142
	v_fmac_f32_e32 v132, v138, v138
	v_add_f32_e32 v121, v121, v132
	v_add_f32_e32 v120, v120, v121
	v_mul_f32_e32 v121, v137, v137
	v_mul_f32_e32 v132, v139, v139
	v_fmac_f32_e32 v121, v136, v136
	v_fmac_f32_e32 v132, v134, v134
	v_add_f32_e32 v121, v121, v132
	v_mul_f32_e32 v132, v208, v208
	v_mul_f32_e32 v133, v123, v123
	v_fmac_f32_e32 v132, v135, v135
	v_fmac_f32_e32 v133, v122, v122
	v_add_f32_e32 v132, v132, v133
	v_add_f32_e32 v121, v121, v132
	v_and_b32_e32 v132, 64, v203
	v_add_f32_e32 v121, v120, v121
	v_xor_b32_e32 v120, 16, v203
	v_add_u32_e32 v133, 64, v132
	v_cmp_lt_i32_e32 vcc, v120, v133
	s_nop 1
	v_cndmask_b32_e32 v120, v203, v120, vcc
	v_lshlrev_b32_e32 v132, 2, v120
	v_mov_b32_e32 v210, v121
	s_nop 1
	v_permlane16_swap_b32_e32 v121, v210
	v_or_b32_e32 v120, s37, v198
	s_waitcnt lgkmcnt(0)
	v_add_f32_e32 v210, v121, v210
	v_xor_b32_e32 v121, 32, v203
	v_cmp_lt_i32_e32 vcc, v121, v133
	s_nop 1
	v_cndmask_b32_e32 v121, v203, v121, vcc
	v_lshlrev_b32_e32 v133, 2, v121
	v_mov_b32_e32 v211, v210
	s_nop 1
	v_permlane32_swap_b32_e32 v210, v211
	s_and_saveexec_b64 s[46:47], s[4:5]
	s_cbranch_execz .LBB0_509
	v_ashrrev_i32_e32 v121, 31, v120
	v_lshlrev_b64 v[212:213], 6, v[120:121]
	v_lshl_add_u64 v[212:213], s[18:19], 0, v[212:213]
	v_lshl_add_u64 v[212:213], s[44:45], 2, v[212:213]
	s_lshl_b32 s10, s59, 2
	v_lshl_add_u64 v[212:213], v[212:213], 0, s[10:11]
	s_waitcnt lgkmcnt(0)
	v_add_f32_e32 v121, v210, v211
	global_store_dword v[212:213], v121, off
.LBB0_509:
	s_or_b64 exec, exec, s[46:47]
	v_cvt_pk_bf16_f32 v140, v140, v206
	v_cvt_pk_bf16_f32 v141, v141, v143
	v_cvt_pk_bf16_f32 v142, v142, v207
	v_cvt_pk_bf16_f32 v143, v138, v209
	v_cvt_pk_bf16_f32 v136, v136, v137
	v_cvt_pk_bf16_f32 v137, v134, v139
	v_cvt_pk_bf16_f32 v138, v135, v208
	v_cvt_pk_bf16_f32 v139, v122, v123
	ds_write_b128 v204, v[140:143]
	ds_write_b128 v204, v[136:139] offset:64
	ds_read_b128 v[134:137], v205
	ds_read_b128 v[138:141], v205 offset:1152
	v_lshl_add_u64 v[122:123], v[196:197], 1, s[20:21]
	s_waitcnt lgkmcnt(1)
	global_store_dwordx4 v[122:123], v[134:137], off nt
	s_nop 1
	v_add_co_u32_e32 v134, vcc, s58, v122
	s_nop 1
	v_addc_co_u32_e32 v135, vcc, 0, v123, vcc
	s_waitcnt lgkmcnt(0)
	global_store_dwordx4 v[134:135], v[138:141], off nt
	ds_write_b128 v205, v[176:179]
	ds_write_b128 v205, v[180:183] offset:1152
	ds_read_b128 v[134:137], v204
	ds_read_b128 v[138:141], v204 offset:64
	s_waitcnt lgkmcnt(1)
	v_lshlrev_b32_e32 v121, 16, v134
	v_add_f32_e32 v116, v116, v121
	v_and_b32_e32 v121, 0xffff0000, v134
	v_add_f32_e32 v121, v117, v121
	v_lshlrev_b32_e32 v117, 16, v135
	v_add_f32_e32 v117, v118, v117
	v_and_b32_e32 v118, 0xffff0000, v135
	v_add_f32_e32 v118, v119, v118
	v_lshlrev_b32_e32 v119, 16, v136
	v_add_f32_e32 v112, v112, v119
	v_and_b32_e32 v119, 0xffff0000, v136
	v_add_f32_e32 v119, v113, v119
	v_lshlrev_b32_e32 v113, 16, v137
	v_add_f32_e32 v114, v114, v113
	v_and_b32_e32 v113, 0xffff0000, v137
	v_add_f32_e32 v115, v115, v113
	s_waitcnt lgkmcnt(0)
	v_lshlrev_b32_e32 v113, 16, v138
	v_add_f32_e32 v100, v100, v113
	v_and_b32_e32 v113, 0xffff0000, v138
	v_add_f32_e32 v113, v101, v113
	v_lshlrev_b32_e32 v101, 16, v139
	v_add_f32_e32 v101, v102, v101
	v_and_b32_e32 v102, 0xffff0000, v139
	v_add_f32_e32 v102, v103, v102
	v_lshlrev_b32_e32 v103, 16, v140
	v_add_f32_e32 v96, v96, v103
	v_and_b32_e32 v103, 0xffff0000, v140
	v_add_f32_e32 v103, v97, v103
	v_lshlrev_b32_e32 v97, 16, v141
	v_add_f32_e32 v97, v98, v97
	v_and_b32_e32 v98, 0xffff0000, v141
	v_add_f32_e32 v98, v99, v98
	v_mul_f32_e32 v99, v121, v121
	v_mul_f32_e32 v134, v118, v118
	v_fmac_f32_e32 v99, v116, v116
	v_fmac_f32_e32 v134, v117, v117
	v_add_f32_e32 v99, v99, v134
	v_mul_f32_e32 v134, v119, v119
	v_mul_f32_e32 v135, v115, v115
	v_fmac_f32_e32 v134, v112, v112
	v_fmac_f32_e32 v135, v114, v114
	v_add_f32_e32 v134, v134, v135
	v_add_f32_e32 v99, v99, v134
	v_mul_f32_e32 v134, v113, v113
	v_mul_f32_e32 v135, v102, v102
	v_fmac_f32_e32 v134, v100, v100
	v_fmac_f32_e32 v135, v101, v101
	v_add_f32_e32 v134, v134, v135
	v_mul_f32_e32 v135, v103, v103
	v_mul_f32_e32 v136, v98, v98
	v_fmac_f32_e32 v135, v96, v96
	v_fmac_f32_e32 v136, v97, v97
	v_add_f32_e32 v135, v135, v136
	v_add_f32_e32 v134, v134, v135
	v_add_f32_e32 v99, v99, v134
	v_mov_b32_e32 v134, v99
	s_nop 1
	v_permlane16_swap_b32_e32 v99, v134
	s_waitcnt lgkmcnt(0)
	v_add_f32_e32 v99, v99, v134
	v_mov_b32_e32 v134, v99
	s_nop 1
	v_permlane32_swap_b32_e32 v99, v134
	s_and_saveexec_b64 s[46:47], s[4:5]
	s_cbranch_execz .LBB0_511
	s_waitcnt lgkmcnt(0)
	v_add_f32_e32 v99, v99, v134
	v_or_b32_e32 v134, 16, v120
	v_ashrrev_i32_e32 v135, 31, v134
	v_lshlrev_b64 v[134:135], 6, v[134:135]
	v_lshl_add_u64 v[134:135], s[18:19], 0, v[134:135]
	v_lshl_add_u64 v[134:135], s[44:45], 2, v[134:135]
	s_lshl_b32 s10, s59, 2
	v_lshl_add_u64 v[134:135], v[134:135], 0, s[10:11]
	global_store_dword v[134:135], v99, off
.LBB0_511:
	s_or_b64 exec, exec, s[46:47]
	v_cvt_pk_bf16_f32 v116, v116, v121
	v_cvt_pk_bf16_f32 v117, v117, v118
	v_cvt_pk_bf16_f32 v118, v112, v119
	v_cvt_pk_bf16_f32 v119, v114, v115
	v_cvt_pk_bf16_f32 v100, v100, v113
	v_cvt_pk_bf16_f32 v101, v101, v102
	v_cvt_pk_bf16_f32 v102, v96, v103
	v_cvt_pk_bf16_f32 v103, v97, v98
	ds_write_b128 v204, v[116:119]
	ds_write_b128 v204, v[100:103] offset:64
	ds_read_b128 v[96:99], v205
	ds_read_b128 v[100:103], v205 offset:1152
	v_add_co_u32_e32 v112, vcc, s64, v122
	s_nop 1
	v_addc_co_u32_e32 v113, vcc, 0, v123, vcc
	s_waitcnt lgkmcnt(1)
	global_store_dwordx4 v[112:113], v[96:99], off nt
	s_nop 1
	v_add_co_u32_e32 v96, vcc, s71, v122
	s_nop 1
	v_addc_co_u32_e32 v97, vcc, 0, v123, vcc
	s_waitcnt lgkmcnt(0)
	global_store_dwordx4 v[96:97], v[100:103], off nt
	ds_write_b128 v205, v[168:171]
	ds_write_b128 v205, v[172:175] offset:1152
	ds_read_b128 v[96:99], v204
	ds_read_b128 v[100:103], v204 offset:64
	s_waitcnt lgkmcnt(1)
	v_lshlrev_b32_e32 v112, 16, v96
	v_and_b32_e32 v96, 0xffff0000, v96
	v_add_f32_e32 v96, v93, v96
	v_lshlrev_b32_e32 v93, 16, v97
	v_add_f32_e32 v93, v94, v93
	v_and_b32_e32 v94, 0xffff0000, v97
	v_add_f32_e32 v94, v95, v94
	v_lshlrev_b32_e32 v95, 16, v98
	v_add_f32_e32 v88, v88, v95
	v_and_b32_e32 v95, 0xffff0000, v98
	v_add_f32_e32 v95, v89, v95
	v_lshlrev_b32_e32 v89, 16, v99
	v_add_f32_e32 v90, v90, v89
	v_and_b32_e32 v89, 0xffff0000, v99
	v_add_f32_e32 v91, v91, v89
	s_waitcnt lgkmcnt(0)
	v_lshlrev_b32_e32 v89, 16, v100
	v_add_f32_e32 v84, v84, v89
	v_and_b32_e32 v89, 0xffff0000, v100
	v_add_f32_e32 v89, v85, v89
	v_lshlrev_b32_e32 v85, 16, v101
	v_add_f32_e32 v85, v86, v85
	v_and_b32_e32 v86, 0xffff0000, v101
	v_add_f32_e32 v86, v87, v86
	v_lshlrev_b32_e32 v87, 16, v102
	v_add_f32_e32 v80, v80, v87
	v_and_b32_e32 v87, 0xffff0000, v102
	v_add_f32_e32 v87, v81, v87
	v_lshlrev_b32_e32 v81, 16, v103
	v_add_f32_e32 v81, v82, v81
	v_and_b32_e32 v82, 0xffff0000, v103
	v_add_f32_e32 v92, v92, v112
	v_add_f32_e32 v82, v83, v82
	v_mul_f32_e32 v83, v96, v96
	v_mul_f32_e32 v97, v94, v94
	v_fmac_f32_e32 v83, v92, v92
	v_fmac_f32_e32 v97, v93, v93
	v_add_f32_e32 v83, v83, v97
	v_mul_f32_e32 v97, v95, v95
	v_mul_f32_e32 v98, v91, v91
	v_fmac_f32_e32 v97, v88, v88
	v_fmac_f32_e32 v98, v90, v90
	v_add_f32_e32 v97, v97, v98
	v_add_f32_e32 v83, v83, v97
	v_mul_f32_e32 v97, v89, v89
	v_mul_f32_e32 v98, v86, v86
	v_fmac_f32_e32 v97, v84, v84
	v_fmac_f32_e32 v98, v85, v85
	v_add_f32_e32 v97, v97, v98
	v_mul_f32_e32 v98, v87, v87
	v_mul_f32_e32 v99, v82, v82
	v_fmac_f32_e32 v98, v80, v80
	v_fmac_f32_e32 v99, v81, v81
	v_add_f32_e32 v98, v98, v99
	v_add_f32_e32 v97, v97, v98
	v_add_f32_e32 v83, v83, v97
	v_mov_b32_e32 v97, v83
	s_nop 1
	v_permlane16_swap_b32_e32 v83, v97
	s_waitcnt lgkmcnt(0)
	v_add_f32_e32 v83, v83, v97
	v_mov_b32_e32 v97, v83
	s_nop 1
	v_permlane32_swap_b32_e32 v83, v97
	s_and_saveexec_b64 s[46:47], s[4:5]
	s_cbranch_execz .LBB0_513
	v_or_b32_e32 v98, 32, v120
	v_ashrrev_i32_e32 v99, 31, v98
	v_lshlrev_b64 v[98:99], 6, v[98:99]
	v_lshl_add_u64 v[98:99], s[18:19], 0, v[98:99]
	v_lshl_add_u64 v[98:99], s[44:45], 2, v[98:99]
	s_lshl_b32 s10, s59, 2
	s_waitcnt lgkmcnt(0)
	v_add_f32_e32 v83, v83, v97
	v_lshl_add_u64 v[98:99], v[98:99], 0, s[10:11]
	global_store_dword v[98:99], v83, off
.LBB0_513:
	s_or_b64 exec, exec, s[46:47]
	v_cvt_pk_bf16_f32 v92, v92, v96
	v_cvt_pk_bf16_f32 v93, v93, v94
	v_cvt_pk_bf16_f32 v94, v88, v95
	v_cvt_pk_bf16_f32 v95, v90, v91
	v_cvt_pk_bf16_f32 v84, v84, v89
	v_cvt_pk_bf16_f32 v85, v85, v86
	v_cvt_pk_bf16_f32 v86, v80, v87
	v_cvt_pk_bf16_f32 v87, v81, v82
	ds_write_b128 v204, v[92:95]
	ds_write_b128 v204, v[84:87] offset:64
	ds_read_b128 v[80:83], v205
	ds_read_b128 v[84:87], v205 offset:1152
	v_add_co_u32_e32 v88, vcc, s56, v122
	s_nop 1
	v_addc_co_u32_e32 v89, vcc, 0, v123, vcc
	s_waitcnt lgkmcnt(1)
	global_store_dwordx4 v[88:89], v[80:83], off nt
	s_nop 1
	v_add_co_u32_e32 v80, vcc, s57, v122
	s_nop 1
	v_addc_co_u32_e32 v81, vcc, 0, v123, vcc
	s_waitcnt lgkmcnt(0)
	global_store_dwordx4 v[80:81], v[84:87], off nt
	ds_write_b128 v205, v[160:163]
	ds_write_b128 v205, v[164:167] offset:1152
	ds_read_b128 v[80:83], v204
	ds_read_b128 v[84:87], v204 offset:64
	s_waitcnt lgkmcnt(1)
	v_lshlrev_b32_e32 v88, 16, v80
	v_and_b32_e32 v80, 0xffff0000, v80
	v_add_f32_e32 v80, v77, v80
	v_lshlrev_b32_e32 v77, 16, v81
	v_add_f32_e32 v77, v78, v77
	v_and_b32_e32 v78, 0xffff0000, v81
	v_add_f32_e32 v78, v79, v78
	v_lshlrev_b32_e32 v79, 16, v82
	v_add_f32_e32 v72, v72, v79
	v_and_b32_e32 v79, 0xffff0000, v82
	v_add_f32_e32 v79, v73, v79
	v_lshlrev_b32_e32 v73, 16, v83
	v_add_f32_e32 v74, v74, v73
	v_and_b32_e32 v73, 0xffff0000, v83
	v_add_f32_e32 v75, v75, v73
	s_waitcnt lgkmcnt(0)
	v_lshlrev_b32_e32 v73, 16, v84
	v_add_f32_e32 v68, v68, v73
	v_and_b32_e32 v73, 0xffff0000, v84
	v_add_f32_e32 v73, v69, v73
	v_lshlrev_b32_e32 v69, 16, v85
	v_add_f32_e32 v69, v70, v69
	v_and_b32_e32 v70, 0xffff0000, v85
	v_add_f32_e32 v70, v71, v70
	v_lshlrev_b32_e32 v71, 16, v86
	v_add_f32_e32 v64, v64, v71
	v_and_b32_e32 v71, 0xffff0000, v86
	v_add_f32_e32 v71, v65, v71
	v_lshlrev_b32_e32 v65, 16, v87
	v_add_f32_e32 v65, v66, v65
	v_and_b32_e32 v66, 0xffff0000, v87
	v_add_f32_e32 v76, v76, v88
	v_add_f32_e32 v66, v67, v66
	v_mul_f32_e32 v67, v80, v80
	v_mul_f32_e32 v81, v78, v78
	v_fmac_f32_e32 v67, v76, v76
	v_fmac_f32_e32 v81, v77, v77
	v_add_f32_e32 v67, v67, v81
	v_mul_f32_e32 v81, v79, v79
	v_mul_f32_e32 v82, v75, v75
	v_fmac_f32_e32 v81, v72, v72
	v_fmac_f32_e32 v82, v74, v74
	v_add_f32_e32 v81, v81, v82
	v_add_f32_e32 v67, v67, v81
	v_mul_f32_e32 v81, v73, v73
	v_mul_f32_e32 v82, v70, v70
	v_fmac_f32_e32 v81, v68, v68
	v_fmac_f32_e32 v82, v69, v69
	v_add_f32_e32 v81, v81, v82
	v_mul_f32_e32 v82, v71, v71
	v_mul_f32_e32 v83, v66, v66
	v_fmac_f32_e32 v82, v64, v64
	v_fmac_f32_e32 v83, v65, v65
	v_add_f32_e32 v82, v82, v83
	v_add_f32_e32 v81, v81, v82
	v_add_f32_e32 v67, v67, v81
	v_mov_b32_e32 v81, v67
	s_nop 1
	v_permlane16_swap_b32_e32 v67, v81
	s_waitcnt lgkmcnt(0)
	v_add_f32_e32 v67, v67, v81
	v_mov_b32_e32 v81, v67
	s_nop 1
	v_permlane32_swap_b32_e32 v67, v81
	s_and_saveexec_b64 s[46:47], s[4:5]
	s_cbranch_execz .LBB0_515
	v_or_b32_e32 v82, 48, v120
	v_ashrrev_i32_e32 v83, 31, v82
	v_lshlrev_b64 v[82:83], 6, v[82:83]
	v_lshl_add_u64 v[82:83], s[18:19], 0, v[82:83]
	v_lshl_add_u64 v[82:83], s[44:45], 2, v[82:83]
	s_lshl_b32 s10, s59, 2
	s_waitcnt lgkmcnt(0)
	v_add_f32_e32 v67, v67, v81
	v_lshl_add_u64 v[82:83], v[82:83], 0, s[10:11]
	global_store_dword v[82:83], v67, off
.LBB0_515:
	s_or_b64 exec, exec, s[46:47]
	v_cvt_pk_bf16_f32 v76, v76, v80
	v_cvt_pk_bf16_f32 v77, v77, v78
	v_cvt_pk_bf16_f32 v78, v72, v79
	v_cvt_pk_bf16_f32 v79, v74, v75
	v_cvt_pk_bf16_f32 v68, v68, v73
	v_cvt_pk_bf16_f32 v69, v69, v70
	v_cvt_pk_bf16_f32 v70, v64, v71
	v_cvt_pk_bf16_f32 v71, v65, v66
	ds_write_b128 v204, v[76:79]
	ds_write_b128 v204, v[68:71] offset:64
	ds_read_b128 v[64:67], v205
	ds_read_b128 v[68:71], v205 offset:1152
	v_add_co_u32_e32 v72, vcc, s63, v122
	s_nop 1
	v_addc_co_u32_e32 v73, vcc, 0, v123, vcc
	s_waitcnt lgkmcnt(1)
	global_store_dwordx4 v[72:73], v[64:67], off nt
	s_nop 1
	v_add_co_u32_e32 v64, vcc, s65, v122
	s_nop 1
	v_addc_co_u32_e32 v65, vcc, 0, v123, vcc
	s_waitcnt lgkmcnt(0)
	global_store_dwordx4 v[64:65], v[68:71], off nt
	ds_write_b128 v205, v[152:155]
	ds_write_b128 v205, v[156:159] offset:1152
	ds_read_b128 v[64:67], v204
	ds_read_b128 v[68:71], v204 offset:64
	s_waitcnt lgkmcnt(1)
	v_lshlrev_b32_e32 v72, 16, v64
	v_and_b32_e32 v64, 0xffff0000, v64
	v_add_f32_e32 v64, v61, v64
	v_lshlrev_b32_e32 v61, 16, v65
	v_add_f32_e32 v61, v62, v61
	v_and_b32_e32 v62, 0xffff0000, v65
	v_add_f32_e32 v62, v63, v62
	v_lshlrev_b32_e32 v63, 16, v66
	v_add_f32_e32 v56, v56, v63
	v_and_b32_e32 v63, 0xffff0000, v66
	v_add_f32_e32 v63, v57, v63
	v_lshlrev_b32_e32 v57, 16, v67
	v_add_f32_e32 v58, v58, v57
	v_and_b32_e32 v57, 0xffff0000, v67
	v_add_f32_e32 v59, v59, v57
	s_waitcnt lgkmcnt(0)
	v_lshlrev_b32_e32 v57, 16, v68
	v_add_f32_e32 v52, v52, v57
	v_and_b32_e32 v57, 0xffff0000, v68
	v_add_f32_e32 v57, v53, v57
	v_lshlrev_b32_e32 v53, 16, v69
	v_add_f32_e32 v53, v54, v53
	v_and_b32_e32 v54, 0xffff0000, v69
	v_add_f32_e32 v54, v55, v54
	v_lshlrev_b32_e32 v55, 16, v70
	v_add_f32_e32 v48, v48, v55
	v_and_b32_e32 v55, 0xffff0000, v70
	v_add_f32_e32 v55, v49, v55
	v_lshlrev_b32_e32 v49, 16, v71
	v_add_f32_e32 v49, v50, v49
	v_and_b32_e32 v50, 0xffff0000, v71
	v_add_f32_e32 v60, v60, v72
	v_add_f32_e32 v50, v51, v50
	v_mul_f32_e32 v51, v64, v64
	v_mul_f32_e32 v65, v62, v62
	v_fmac_f32_e32 v51, v60, v60
	v_fmac_f32_e32 v65, v61, v61
	v_add_f32_e32 v51, v51, v65
	v_mul_f32_e32 v65, v63, v63
	v_mul_f32_e32 v66, v59, v59
	v_fmac_f32_e32 v65, v56, v56
	v_fmac_f32_e32 v66, v58, v58
	v_add_f32_e32 v65, v65, v66
	v_add_f32_e32 v51, v51, v65
	v_mul_f32_e32 v65, v57, v57
	v_mul_f32_e32 v66, v54, v54
	v_fmac_f32_e32 v65, v52, v52
	v_fmac_f32_e32 v66, v53, v53
	v_add_f32_e32 v65, v65, v66
	v_mul_f32_e32 v66, v55, v55
	v_mul_f32_e32 v67, v50, v50
	v_fmac_f32_e32 v66, v48, v48
	v_fmac_f32_e32 v67, v49, v49
	v_add_f32_e32 v66, v66, v67
	v_add_f32_e32 v65, v65, v66
	v_add_f32_e32 v51, v51, v65
	v_mov_b32_e32 v65, v51
	s_nop 1
	v_permlane16_swap_b32_e32 v51, v65
	s_waitcnt lgkmcnt(0)
	v_add_f32_e32 v51, v51, v65
	v_mov_b32_e32 v65, v51
	s_nop 1
	v_permlane32_swap_b32_e32 v51, v65
	s_and_saveexec_b64 s[46:47], s[4:5]
	s_cbranch_execz .LBB0_517
	v_add_u32_e32 v66, 0x80, v120
	v_ashrrev_i32_e32 v67, 31, v66
	v_lshlrev_b64 v[66:67], 6, v[66:67]
	v_lshl_add_u64 v[66:67], s[18:19], 0, v[66:67]
	v_lshl_add_u64 v[66:67], s[44:45], 2, v[66:67]
	s_lshl_b32 s10, s59, 2
	s_waitcnt lgkmcnt(0)
	v_add_f32_e32 v51, v51, v65
	v_lshl_add_u64 v[66:67], v[66:67], 0, s[10:11]
	global_store_dword v[66:67], v51, off
.LBB0_517:
	s_or_b64 exec, exec, s[46:47]
	v_cvt_pk_bf16_f32 v60, v60, v64
	v_cvt_pk_bf16_f32 v61, v61, v62
	v_cvt_pk_bf16_f32 v62, v56, v63
	v_cvt_pk_bf16_f32 v63, v58, v59
	v_cvt_pk_bf16_f32 v52, v52, v57
	v_cvt_pk_bf16_f32 v53, v53, v54
	v_cvt_pk_bf16_f32 v54, v48, v55
	v_cvt_pk_bf16_f32 v55, v49, v50
	ds_write_b128 v204, v[60:63]
	ds_write_b128 v204, v[52:55] offset:64
	ds_read_b128 v[48:51], v205
	ds_read_b128 v[52:55], v205 offset:1152
	v_add_co_u32_e32 v56, vcc, s72, v122
	s_nop 1
	v_addc_co_u32_e32 v57, vcc, 0, v123, vcc
	s_waitcnt lgkmcnt(1)
	global_store_dwordx4 v[56:57], v[48:51], off nt
	s_nop 1
	v_add_co_u32_e32 v48, vcc, s73, v122
	s_nop 1
	v_addc_co_u32_e32 v49, vcc, 0, v123, vcc
	s_waitcnt lgkmcnt(0)
	global_store_dwordx4 v[48:49], v[52:55], off nt
	ds_write_b128 v205, v[144:147]
	ds_write_b128 v205, v[148:151] offset:1152
	ds_read_b128 v[48:51], v204
	ds_read_b128 v[52:55], v204 offset:64
	s_waitcnt lgkmcnt(1)
	v_lshlrev_b32_e32 v56, 16, v48
	v_and_b32_e32 v48, 0xffff0000, v48
	v_add_f32_e32 v48, v45, v48
	v_lshlrev_b32_e32 v45, 16, v49
	v_add_f32_e32 v45, v46, v45
	v_and_b32_e32 v46, 0xffff0000, v49
	v_add_f32_e32 v46, v47, v46
	v_lshlrev_b32_e32 v47, 16, v50
	v_add_f32_e32 v40, v40, v47
	v_and_b32_e32 v47, 0xffff0000, v50
	v_add_f32_e32 v47, v41, v47
	v_lshlrev_b32_e32 v41, 16, v51
	v_add_f32_e32 v42, v42, v41
	v_and_b32_e32 v41, 0xffff0000, v51
	v_add_f32_e32 v43, v43, v41
	s_waitcnt lgkmcnt(0)
	v_lshlrev_b32_e32 v41, 16, v52
	v_add_f32_e32 v36, v36, v41
	v_and_b32_e32 v41, 0xffff0000, v52
	v_add_f32_e32 v41, v37, v41
	v_lshlrev_b32_e32 v37, 16, v53
	v_add_f32_e32 v37, v38, v37
	v_and_b32_e32 v38, 0xffff0000, v53
	v_add_f32_e32 v38, v39, v38
	v_lshlrev_b32_e32 v39, 16, v54
	v_add_f32_e32 v32, v32, v39
	v_and_b32_e32 v39, 0xffff0000, v54
	v_add_f32_e32 v39, v33, v39
	v_lshlrev_b32_e32 v33, 16, v55
	v_add_f32_e32 v33, v34, v33
	v_and_b32_e32 v34, 0xffff0000, v55
	v_add_f32_e32 v44, v44, v56
	v_add_f32_e32 v34, v35, v34
	v_mul_f32_e32 v35, v48, v48
	v_mul_f32_e32 v49, v46, v46
	v_fmac_f32_e32 v35, v44, v44
	v_fmac_f32_e32 v49, v45, v45
	v_add_f32_e32 v35, v35, v49
	v_mul_f32_e32 v49, v47, v47
	v_mul_f32_e32 v50, v43, v43
	v_fmac_f32_e32 v49, v40, v40
	v_fmac_f32_e32 v50, v42, v42
	v_add_f32_e32 v49, v49, v50
	v_add_f32_e32 v35, v35, v49
	v_mul_f32_e32 v49, v41, v41
	v_mul_f32_e32 v50, v38, v38
	v_fmac_f32_e32 v49, v36, v36
	v_fmac_f32_e32 v50, v37, v37
	v_add_f32_e32 v49, v49, v50
	v_mul_f32_e32 v50, v39, v39
	v_mul_f32_e32 v51, v34, v34
	v_fmac_f32_e32 v50, v32, v32
	v_fmac_f32_e32 v51, v33, v33
	v_add_f32_e32 v50, v50, v51
	v_add_f32_e32 v49, v49, v50
	v_add_f32_e32 v35, v35, v49
	v_mov_b32_e32 v49, v35
	s_nop 1
	v_permlane16_swap_b32_e32 v35, v49
	s_waitcnt lgkmcnt(0)
	v_add_f32_e32 v35, v35, v49
	v_mov_b32_e32 v49, v35
	s_nop 1
	v_permlane32_swap_b32_e32 v35, v49
	s_and_saveexec_b64 s[46:47], s[4:5]
	s_cbranch_execz .LBB0_519
	v_add_u32_e32 v50, 0x90, v120
	v_ashrrev_i32_e32 v51, 31, v50
	v_lshlrev_b64 v[50:51], 6, v[50:51]
	v_lshl_add_u64 v[50:51], s[18:19], 0, v[50:51]
	v_lshl_add_u64 v[50:51], s[44:45], 2, v[50:51]
	s_lshl_b32 s10, s59, 2
	s_waitcnt lgkmcnt(0)
	v_add_f32_e32 v35, v35, v49
	v_lshl_add_u64 v[50:51], v[50:51], 0, s[10:11]
	global_store_dword v[50:51], v35, off
.LBB0_519:
	s_or_b64 exec, exec, s[46:47]
	v_cvt_pk_bf16_f32 v44, v44, v48
	v_cvt_pk_bf16_f32 v45, v45, v46
	v_cvt_pk_bf16_f32 v46, v40, v47
	v_cvt_pk_bf16_f32 v47, v42, v43
	v_cvt_pk_bf16_f32 v36, v36, v41
	v_cvt_pk_bf16_f32 v37, v37, v38
	v_cvt_pk_bf16_f32 v38, v32, v39
	v_cvt_pk_bf16_f32 v39, v33, v34
	ds_write_b128 v204, v[44:47]
	ds_write_b128 v204, v[36:39] offset:64
	ds_read_b128 v[32:35], v205
	ds_read_b128 v[36:39], v205 offset:1152
	v_add_co_u32_e32 v40, vcc, s74, v122
	s_nop 1
	v_addc_co_u32_e32 v41, vcc, 0, v123, vcc
	s_waitcnt lgkmcnt(1)
	global_store_dwordx4 v[40:41], v[32:35], off nt
	s_nop 1
	v_add_co_u32_e32 v32, vcc, s75, v122
	s_nop 1
	v_addc_co_u32_e32 v33, vcc, 0, v123, vcc
	s_waitcnt lgkmcnt(0)
	global_store_dwordx4 v[32:33], v[36:39], off nt
	ds_write_b128 v205, v[124:127]
	ds_write_b128 v205, v[128:131] offset:1152
	ds_read_b128 v[32:35], v204
	ds_read_b128 v[36:39], v204 offset:64
	s_waitcnt lgkmcnt(1)
	v_lshlrev_b32_e32 v40, 16, v32
	v_and_b32_e32 v32, 0xffff0000, v32
	v_add_f32_e32 v32, v29, v32
	v_lshlrev_b32_e32 v29, 16, v33
	v_add_f32_e32 v29, v30, v29
	v_and_b32_e32 v30, 0xffff0000, v33
	v_add_f32_e32 v30, v31, v30
	v_lshlrev_b32_e32 v31, 16, v34
	v_add_f32_e32 v24, v24, v31
	v_and_b32_e32 v31, 0xffff0000, v34
	v_add_f32_e32 v31, v25, v31
	v_lshlrev_b32_e32 v25, 16, v35
	v_add_f32_e32 v26, v26, v25
	v_and_b32_e32 v25, 0xffff0000, v35
	v_add_f32_e32 v27, v27, v25
	s_waitcnt lgkmcnt(0)
	v_lshlrev_b32_e32 v25, 16, v36
	v_add_f32_e32 v20, v20, v25
	v_and_b32_e32 v25, 0xffff0000, v36
	v_add_f32_e32 v25, v21, v25
	v_lshlrev_b32_e32 v21, 16, v37
	v_add_f32_e32 v21, v22, v21
	v_and_b32_e32 v22, 0xffff0000, v37
	v_add_f32_e32 v22, v23, v22
	v_lshlrev_b32_e32 v23, 16, v38
	v_add_f32_e32 v16, v16, v23
	v_and_b32_e32 v23, 0xffff0000, v38
	v_add_f32_e32 v23, v17, v23
	v_lshlrev_b32_e32 v17, 16, v39
	v_add_f32_e32 v17, v18, v17
	v_and_b32_e32 v18, 0xffff0000, v39
	v_add_f32_e32 v28, v28, v40
	v_add_f32_e32 v18, v19, v18
	v_mul_f32_e32 v19, v32, v32
	v_mul_f32_e32 v33, v30, v30
	v_fmac_f32_e32 v19, v28, v28
	v_fmac_f32_e32 v33, v29, v29
	v_add_f32_e32 v19, v19, v33
	v_mul_f32_e32 v33, v31, v31
	v_mul_f32_e32 v34, v27, v27
	v_fmac_f32_e32 v33, v24, v24
	v_fmac_f32_e32 v34, v26, v26
	v_add_f32_e32 v33, v33, v34
	v_add_f32_e32 v19, v19, v33
	v_mul_f32_e32 v33, v25, v25
	v_mul_f32_e32 v34, v22, v22
	v_fmac_f32_e32 v33, v20, v20
	v_fmac_f32_e32 v34, v21, v21
	v_add_f32_e32 v33, v33, v34
	v_mul_f32_e32 v34, v23, v23
	v_mul_f32_e32 v35, v18, v18
	v_fmac_f32_e32 v34, v16, v16
	v_fmac_f32_e32 v35, v17, v17
	v_add_f32_e32 v34, v34, v35
	v_add_f32_e32 v33, v33, v34
	v_add_f32_e32 v19, v19, v33
	v_mov_b32_e32 v33, v19
	s_nop 1
	v_permlane16_swap_b32_e32 v19, v33
	s_waitcnt lgkmcnt(0)
	v_add_f32_e32 v19, v19, v33
	v_mov_b32_e32 v33, v19
	s_nop 1
	v_permlane32_swap_b32_e32 v19, v33
	s_and_saveexec_b64 s[46:47], s[4:5]
	s_cbranch_execz .LBB0_521
	v_add_u32_e32 v34, 0xa0, v120
	v_ashrrev_i32_e32 v35, 31, v34
	v_lshlrev_b64 v[34:35], 6, v[34:35]
	v_lshl_add_u64 v[34:35], s[18:19], 0, v[34:35]
	v_lshl_add_u64 v[34:35], s[44:45], 2, v[34:35]
	s_lshl_b32 s10, s59, 2
	s_waitcnt lgkmcnt(0)
	v_add_f32_e32 v19, v19, v33
	v_lshl_add_u64 v[34:35], v[34:35], 0, s[10:11]
	global_store_dword v[34:35], v19, off
.LBB0_521:
	s_or_b64 exec, exec, s[46:47]
	v_cvt_pk_bf16_f32 v28, v28, v32
	v_cvt_pk_bf16_f32 v29, v29, v30
	v_cvt_pk_bf16_f32 v30, v24, v31
	v_cvt_pk_bf16_f32 v31, v26, v27
	v_cvt_pk_bf16_f32 v20, v20, v25
	v_cvt_pk_bf16_f32 v21, v21, v22
	v_cvt_pk_bf16_f32 v22, v16, v23
	v_cvt_pk_bf16_f32 v23, v17, v18
	ds_write_b128 v204, v[28:31]
	ds_write_b128 v204, v[20:23] offset:64
	ds_read_b128 v[16:19], v205
	ds_read_b128 v[20:23], v205 offset:1152
	v_add_co_u32_e32 v24, vcc, s79, v122
	s_nop 1
	v_addc_co_u32_e32 v25, vcc, 0, v123, vcc
	s_waitcnt lgkmcnt(1)
	global_store_dwordx4 v[24:25], v[16:19], off nt
	s_nop 1
	v_add_co_u32_e32 v16, vcc, s80, v122
	s_nop 1
	v_addc_co_u32_e32 v17, vcc, 0, v123, vcc
	s_waitcnt lgkmcnt(0)
	global_store_dwordx4 v[16:17], v[20:23], off nt
	ds_write_b128 v205, v[104:107]
	ds_write_b128 v205, v[108:111] offset:1152
	ds_read_b128 v[16:19], v204
	ds_read_b128 v[20:23], v204 offset:64
	s_waitcnt lgkmcnt(1)
	v_lshlrev_b32_e32 v24, 16, v16
	v_and_b32_e32 v16, 0xffff0000, v16
	v_add_f32_e32 v16, v13, v16
	v_lshlrev_b32_e32 v13, 16, v17
	v_add_f32_e32 v13, v14, v13
	v_and_b32_e32 v14, 0xffff0000, v17
	v_add_f32_e32 v14, v15, v14
	v_lshlrev_b32_e32 v15, 16, v18
	v_add_f32_e32 v8, v8, v15
	v_and_b32_e32 v15, 0xffff0000, v18
	v_add_f32_e32 v15, v9, v15
	v_lshlrev_b32_e32 v9, 16, v19
	v_add_f32_e32 v10, v10, v9
	v_and_b32_e32 v9, 0xffff0000, v19
	v_add_f32_e32 v11, v11, v9
	s_waitcnt lgkmcnt(0)
	v_lshlrev_b32_e32 v9, 16, v20
	v_add_f32_e32 v4, v4, v9
	v_and_b32_e32 v9, 0xffff0000, v20
	v_add_f32_e32 v9, v5, v9
	v_lshlrev_b32_e32 v5, 16, v21
	v_add_f32_e32 v5, v6, v5
	v_and_b32_e32 v6, 0xffff0000, v21
	v_add_f32_e32 v6, v7, v6
	v_lshlrev_b32_e32 v7, 16, v22
	v_add_f32_e32 v0, v0, v7
	v_and_b32_e32 v7, 0xffff0000, v22
	v_add_f32_e32 v7, v1, v7
	v_lshlrev_b32_e32 v1, 16, v23
	v_add_f32_e32 v1, v2, v1
	v_and_b32_e32 v2, 0xffff0000, v23
	v_add_f32_e32 v12, v12, v24
	v_add_f32_e32 v2, v3, v2
	v_mul_f32_e32 v3, v16, v16
	v_mul_f32_e32 v17, v14, v14
	v_fmac_f32_e32 v3, v12, v12
	v_fmac_f32_e32 v17, v13, v13
	v_add_f32_e32 v3, v3, v17
	v_mul_f32_e32 v17, v15, v15
	v_mul_f32_e32 v18, v11, v11
	v_fmac_f32_e32 v17, v8, v8
	v_fmac_f32_e32 v18, v10, v10
	v_add_f32_e32 v17, v17, v18
	v_add_f32_e32 v3, v3, v17
	v_mul_f32_e32 v17, v9, v9
	v_mul_f32_e32 v18, v6, v6
	v_fmac_f32_e32 v17, v4, v4
	v_fmac_f32_e32 v18, v5, v5
	v_add_f32_e32 v17, v17, v18
	v_mul_f32_e32 v18, v7, v7
	v_mul_f32_e32 v19, v2, v2
	v_fmac_f32_e32 v18, v0, v0
	v_fmac_f32_e32 v19, v1, v1
	v_add_f32_e32 v18, v18, v19
	v_add_f32_e32 v17, v17, v18
	v_add_f32_e32 v3, v3, v17
	v_mov_b32_e32 v17, v3
	s_nop 1
	v_permlane16_swap_b32_e32 v3, v17
	s_waitcnt lgkmcnt(0)
	v_add_f32_e32 v3, v3, v17
	v_mov_b32_e32 v17, v3
	s_nop 1
	v_permlane32_swap_b32_e32 v3, v17
	s_and_saveexec_b64 s[46:47], s[4:5]
	s_cbranch_execz .LBB0_523
	v_add_u32_e32 v18, 0xb0, v120
	v_ashrrev_i32_e32 v19, 31, v18
	v_lshlrev_b64 v[18:19], 6, v[18:19]
	v_lshl_add_u64 v[18:19], s[18:19], 0, v[18:19]
	v_lshl_add_u64 v[18:19], s[44:45], 2, v[18:19]
	s_lshl_b32 s10, s59, 2
	s_waitcnt lgkmcnt(0)
	v_add_f32_e32 v3, v3, v17
	v_lshl_add_u64 v[18:19], v[18:19], 0, s[10:11]
	global_store_dword v[18:19], v3, off

.LBB0_574:
	s_lshl_b32 s10, s10, 2
	s_add_i32 s66, s10, -4
	s_andn2_b64 vcc, exec, s[68:69]
	s_ashr_i32 s67, s66, 31
	s_cbranch_vccnz .LBB0_580
	v_mul_f32_e32 v128, v125, v125
	v_mul_f32_e32 v129, v127, v127
	v_fmac_f32_e32 v128, v124, v124
	v_fmac_f32_e32 v129, v126, v126
	v_add_f32_e32 v128, v128, v129
	v_mul_f32_e32 v129, v121, v121
	v_mul_f32_e32 v130, v123, v123
	v_fmac_f32_e32 v129, v120, v120
	v_fmac_f32_e32 v130, v122, v122
	v_add_f32_e32 v129, v129, v130
	v_add_f32_e32 v128, v128, v129
	v_mul_f32_e32 v129, v117, v117
	v_mul_f32_e32 v130, v119, v119
	v_fmac_f32_e32 v129, v116, v116
	v_fmac_f32_e32 v130, v118, v118
	v_add_f32_e32 v129, v129, v130
	v_mul_f32_e32 v130, v113, v113
	v_mul_f32_e32 v131, v115, v115
	v_fmac_f32_e32 v130, v112, v112
	v_fmac_f32_e32 v131, v114, v114
	v_add_f32_e32 v130, v130, v131
	v_add_f32_e32 v129, v129, v130
	v_and_b32_e32 v130, 64, v191
	v_add_f32_e32 v128, v128, v129
	v_xor_b32_e32 v129, 16, v191
	v_add_u32_e32 v130, 64, v130
	v_cmp_lt_i32_e32 vcc, v129, v130
	s_nop 1
	v_cndmask_b32_e32 v129, v191, v129, vcc
	v_lshlrev_b32_e32 v129, 2, v129
	v_mov_b32_e32 v129, v128
	s_nop 1
	v_permlane16_swap_b32_e32 v128, v129
	s_waitcnt lgkmcnt(0)
	v_add_f32_e32 v128, v128, v129
	v_xor_b32_e32 v129, 32, v191
	v_cmp_lt_i32_e32 vcc, v129, v130
	s_nop 1
	v_cndmask_b32_e32 v129, v191, v129, vcc
	v_lshlrev_b32_e32 v129, 2, v129
	v_mov_b32_e32 v129, v128
	s_nop 1
	v_permlane32_swap_b32_e32 v128, v129
	s_and_saveexec_b64 s[10:11], s[4:5]
	s_cbranch_execz .LBB0_579
	s_waitcnt lgkmcnt(0)
	v_add_f32_e32 v128, v128, v129
	s_and_b64 vcc, exec, s[64:65]
	s_cbranch_vccz .LBB0_707
	v_lshlrev_b64 v[130:131], 5, v[188:189]
	v_lshl_add_u64 v[130:131], s[40:41], 0, v[130:131]
	v_lshl_add_u64 v[130:131], s[66:67], 2, v[130:131]
	s_lshl_b32 s16, s92, 2
	v_lshl_add_u64 v[130:131], v[130:131], 0, s[16:17]
	global_store_dword v[130:131], v128, off
	s_cbranch_execnz .LBB0_579

.LBB0_590:
	s_andn2_b64 vcc, exec, s[72:73]
	s_cbranch_vccnz .LBB0_596
	v_mul_f32_e32 v112, v109, v109
	v_mul_f32_e32 v113, v111, v111
	v_fmac_f32_e32 v112, v108, v108
	v_fmac_f32_e32 v113, v110, v110
	v_add_f32_e32 v112, v112, v113
	v_mul_f32_e32 v113, v105, v105
	v_mul_f32_e32 v114, v107, v107
	v_fmac_f32_e32 v113, v104, v104
	v_fmac_f32_e32 v114, v106, v106
	v_add_f32_e32 v113, v113, v114
	v_add_f32_e32 v112, v112, v113
	v_mul_f32_e32 v113, v101, v101
	v_mul_f32_e32 v114, v103, v103
	v_fmac_f32_e32 v113, v100, v100
	v_fmac_f32_e32 v114, v102, v102
	v_add_f32_e32 v113, v113, v114
	v_mul_f32_e32 v114, v97, v97
	v_mul_f32_e32 v115, v99, v99
	v_fmac_f32_e32 v114, v96, v96
	v_fmac_f32_e32 v115, v98, v98
	v_add_f32_e32 v114, v114, v115
	v_add_f32_e32 v113, v113, v114
	v_and_b32_e32 v114, 64, v191
	v_add_f32_e32 v112, v112, v113
	v_xor_b32_e32 v113, 16, v191
	v_add_u32_e32 v114, 64, v114
	v_cmp_lt_i32_e32 vcc, v113, v114
	s_nop 1
	v_cndmask_b32_e32 v113, v191, v113, vcc
	v_lshlrev_b32_e32 v113, 2, v113
	v_mov_b32_e32 v113, v112
	s_nop 1
	v_permlane16_swap_b32_e32 v112, v113
	s_waitcnt lgkmcnt(0)
	v_add_f32_e32 v112, v112, v113
	v_xor_b32_e32 v113, 32, v191
	v_cmp_lt_i32_e32 vcc, v113, v114
	s_nop 1
	v_cndmask_b32_e32 v113, v191, v113, vcc
	v_lshlrev_b32_e32 v113, 2, v113
	v_mov_b32_e32 v113, v112
	s_nop 1
	v_permlane32_swap_b32_e32 v112, v113
	s_and_saveexec_b64 s[72:73], s[4:5]
	s_cbranch_execz .LBB0_595
	s_andn2_b64 vcc, exec, s[64:65]
	s_waitcnt lgkmcnt(0)
	v_add_f32_e32 v112, v112, v113
	s_cbranch_vccnz .LBB0_708
	v_lshlrev_b64 v[114:115], 5, v[184:185]
	v_lshl_add_u64 v[114:115], s[40:41], 0, v[114:115]
	v_lshl_add_u64 v[114:115], s[66:67], 2, v[114:115]
	s_lshl_b32 s16, s92, 2
	v_lshl_add_u64 v[114:115], v[114:115], 0, s[16:17]
	global_store_dword v[114:115], v112, off
	s_cbranch_execnz .LBB0_595

.LBB0_606:
	s_andn2_b64 vcc, exec, s[72:73]
	s_cbranch_vccnz .LBB0_612
	s_waitcnt lgkmcnt(1)
	v_mul_f32_e32 v96, v93, v93
	v_mul_f32_e32 v97, v95, v95
	v_fmac_f32_e32 v96, v92, v92
	v_fmac_f32_e32 v97, v94, v94
	v_add_f32_e32 v96, v96, v97
	v_mul_f32_e32 v97, v89, v89
	v_mul_f32_e32 v98, v91, v91
	v_fmac_f32_e32 v97, v88, v88
	v_fmac_f32_e32 v98, v90, v90
	v_add_f32_e32 v97, v97, v98
	v_add_f32_e32 v96, v96, v97
	v_mul_f32_e32 v97, v85, v85
	v_mul_f32_e32 v98, v87, v87
	v_fmac_f32_e32 v97, v84, v84
	v_fmac_f32_e32 v98, v86, v86
	v_add_f32_e32 v97, v97, v98
	v_mul_f32_e32 v98, v81, v81
	v_mul_f32_e32 v99, v83, v83
	v_fmac_f32_e32 v98, v80, v80
	v_fmac_f32_e32 v99, v82, v82
	v_add_f32_e32 v98, v98, v99
	v_add_f32_e32 v97, v97, v98
	v_and_b32_e32 v98, 64, v191
	v_add_f32_e32 v96, v96, v97
	v_xor_b32_e32 v97, 16, v191
	v_add_u32_e32 v98, 64, v98
	v_cmp_lt_i32_e32 vcc, v97, v98
	s_nop 1
	v_cndmask_b32_e32 v97, v191, v97, vcc
	v_lshlrev_b32_e32 v97, 2, v97
	v_mov_b32_e32 v97, v96
	s_nop 1
	v_permlane16_swap_b32_e32 v96, v97
	s_waitcnt lgkmcnt(0)
	v_add_f32_e32 v96, v96, v97
	v_xor_b32_e32 v97, 32, v191
	v_cmp_lt_i32_e32 vcc, v97, v98
	s_nop 1
	v_cndmask_b32_e32 v97, v191, v97, vcc
	v_lshlrev_b32_e32 v97, 2, v97
	v_mov_b32_e32 v97, v96
	s_nop 1
	v_permlane32_swap_b32_e32 v96, v97
	s_and_saveexec_b64 s[72:73], s[4:5]
	s_cbranch_execz .LBB0_611
	s_andn2_b64 vcc, exec, s[64:65]
	s_waitcnt lgkmcnt(0)
	v_add_f32_e32 v96, v96, v97
	s_cbranch_vccnz .LBB0_709
	v_lshlrev_b64 v[98:99], 5, v[180:181]
	v_lshl_add_u64 v[98:99], s[40:41], 0, v[98:99]
	v_lshl_add_u64 v[98:99], s[66:67], 2, v[98:99]
	s_lshl_b32 s16, s92, 2
	v_lshl_add_u64 v[98:99], v[98:99], 0, s[16:17]
	global_store_dword v[98:99], v96, off
	s_cbranch_execnz .LBB0_611

.LBB0_622:
	s_andn2_b64 vcc, exec, s[72:73]
	s_cbranch_vccnz .LBB0_628
	s_waitcnt lgkmcnt(1)
	v_mul_f32_e32 v80, v77, v77
	v_mul_f32_e32 v81, v79, v79
	v_fmac_f32_e32 v80, v76, v76
	v_fmac_f32_e32 v81, v78, v78
	v_add_f32_e32 v80, v80, v81
	v_mul_f32_e32 v81, v73, v73
	v_mul_f32_e32 v82, v75, v75
	v_fmac_f32_e32 v81, v72, v72
	v_fmac_f32_e32 v82, v74, v74
	v_add_f32_e32 v81, v81, v82
	v_add_f32_e32 v80, v80, v81
	v_mul_f32_e32 v81, v69, v69
	v_mul_f32_e32 v82, v71, v71
	v_fmac_f32_e32 v81, v68, v68
	v_fmac_f32_e32 v82, v70, v70
	v_add_f32_e32 v81, v81, v82
	v_mul_f32_e32 v82, v65, v65
	v_mul_f32_e32 v83, v67, v67
	v_fmac_f32_e32 v82, v64, v64
	v_fmac_f32_e32 v83, v66, v66
	v_add_f32_e32 v82, v82, v83
	v_add_f32_e32 v81, v81, v82
	v_and_b32_e32 v82, 64, v191
	v_add_f32_e32 v80, v80, v81
	v_xor_b32_e32 v81, 16, v191
	v_add_u32_e32 v82, 64, v82
	v_cmp_lt_i32_e32 vcc, v81, v82
	s_nop 1
	v_cndmask_b32_e32 v81, v191, v81, vcc
	v_lshlrev_b32_e32 v81, 2, v81
	v_mov_b32_e32 v81, v80
	s_nop 1
	v_permlane16_swap_b32_e32 v80, v81
	s_waitcnt lgkmcnt(0)
	v_add_f32_e32 v80, v80, v81
	v_xor_b32_e32 v81, 32, v191
	v_cmp_lt_i32_e32 vcc, v81, v82
	s_nop 1
	v_cndmask_b32_e32 v81, v191, v81, vcc
	v_lshlrev_b32_e32 v81, 2, v81
	v_mov_b32_e32 v81, v80
	s_nop 1
	v_permlane32_swap_b32_e32 v80, v81
	s_and_saveexec_b64 s[72:73], s[4:5]
	s_cbranch_execz .LBB0_627
	s_andn2_b64 vcc, exec, s[64:65]
	s_waitcnt lgkmcnt(0)
	v_add_f32_e32 v80, v80, v81
	s_cbranch_vccnz .LBB0_710
	v_lshlrev_b64 v[82:83], 5, v[174:175]
	v_lshl_add_u64 v[82:83], s[40:41], 0, v[82:83]
	v_lshl_add_u64 v[82:83], s[66:67], 2, v[82:83]
	s_lshl_b32 s16, s92, 2
	v_lshl_add_u64 v[82:83], v[82:83], 0, s[16:17]
	global_store_dword v[82:83], v80, off
	s_cbranch_execnz .LBB0_627

.LBB0_638:
	s_andn2_b64 vcc, exec, s[72:73]
	s_cbranch_vccnz .LBB0_644
	s_waitcnt lgkmcnt(1)
	v_mul_f32_e32 v64, v61, v61
	v_mul_f32_e32 v65, v63, v63
	v_fmac_f32_e32 v64, v60, v60
	v_fmac_f32_e32 v65, v62, v62
	v_add_f32_e32 v64, v64, v65
	v_mul_f32_e32 v65, v57, v57
	v_mul_f32_e32 v66, v59, v59
	v_fmac_f32_e32 v65, v56, v56
	v_fmac_f32_e32 v66, v58, v58
	v_add_f32_e32 v65, v65, v66
	v_add_f32_e32 v64, v64, v65
	v_mul_f32_e32 v65, v53, v53
	v_mul_f32_e32 v66, v55, v55
	v_fmac_f32_e32 v65, v52, v52
	v_fmac_f32_e32 v66, v54, v54
	v_add_f32_e32 v65, v65, v66
	v_mul_f32_e32 v66, v49, v49
	v_mul_f32_e32 v67, v51, v51
	v_fmac_f32_e32 v66, v48, v48
	v_fmac_f32_e32 v67, v50, v50
	v_add_f32_e32 v66, v66, v67
	v_add_f32_e32 v65, v65, v66
	v_and_b32_e32 v66, 64, v191
	v_add_f32_e32 v64, v64, v65
	v_xor_b32_e32 v65, 16, v191
	v_add_u32_e32 v66, 64, v66
	v_cmp_lt_i32_e32 vcc, v65, v66
	s_nop 1
	v_cndmask_b32_e32 v65, v191, v65, vcc
	v_lshlrev_b32_e32 v65, 2, v65
	v_mov_b32_e32 v65, v64
	s_nop 1
	v_permlane16_swap_b32_e32 v64, v65
	s_waitcnt lgkmcnt(0)
	v_add_f32_e32 v64, v64, v65
	v_xor_b32_e32 v65, 32, v191
	v_cmp_lt_i32_e32 vcc, v65, v66
	s_nop 1
	v_cndmask_b32_e32 v65, v191, v65, vcc
	v_lshlrev_b32_e32 v65, 2, v65
	v_mov_b32_e32 v65, v64
	s_nop 1
	v_permlane32_swap_b32_e32 v64, v65
	s_and_saveexec_b64 s[72:73], s[4:5]
	s_cbranch_execz .LBB0_643
	s_andn2_b64 vcc, exec, s[64:65]
	s_waitcnt lgkmcnt(0)
	v_add_f32_e32 v64, v64, v65
	s_cbranch_vccnz .LBB0_711
	v_lshlrev_b64 v[66:67], 5, v[170:171]
	v_lshl_add_u64 v[66:67], s[40:41], 0, v[66:67]
	v_lshl_add_u64 v[66:67], s[66:67], 2, v[66:67]
	s_lshl_b32 s74, s92, 2
	s_mov_b32 s75, s17
	v_lshl_add_u64 v[66:67], v[66:67], 0, s[74:75]
	global_store_dword v[66:67], v64, off
	s_cbranch_execnz .LBB0_643

.LBB0_654:
	s_andn2_b64 vcc, exec, s[70:71]
	s_cbranch_vccnz .LBB0_660
	s_waitcnt lgkmcnt(1)
	v_mul_f32_e32 v48, v45, v45
	v_mul_f32_e32 v49, v47, v47
	v_fmac_f32_e32 v48, v44, v44
	v_fmac_f32_e32 v49, v46, v46
	v_add_f32_e32 v48, v48, v49
	v_mul_f32_e32 v49, v41, v41
	v_mul_f32_e32 v50, v43, v43
	v_fmac_f32_e32 v49, v40, v40
	v_fmac_f32_e32 v50, v42, v42
	v_add_f32_e32 v49, v49, v50
	v_add_f32_e32 v48, v48, v49
	v_mul_f32_e32 v49, v37, v37
	v_mul_f32_e32 v50, v39, v39
	v_fmac_f32_e32 v49, v36, v36
	v_fmac_f32_e32 v50, v38, v38
	v_add_f32_e32 v49, v49, v50
	v_mul_f32_e32 v50, v33, v33
	v_mul_f32_e32 v51, v35, v35
	v_fmac_f32_e32 v50, v32, v32
	v_fmac_f32_e32 v51, v34, v34
	v_add_f32_e32 v50, v50, v51
	v_add_f32_e32 v49, v49, v50
	v_and_b32_e32 v50, 64, v191
	v_add_f32_e32 v48, v48, v49
	v_xor_b32_e32 v49, 16, v191
	v_add_u32_e32 v50, 64, v50
	v_cmp_lt_i32_e32 vcc, v49, v50
	s_nop 1
	v_cndmask_b32_e32 v49, v191, v49, vcc
	v_lshlrev_b32_e32 v49, 2, v49
	v_mov_b32_e32 v49, v48
	s_nop 1
	v_permlane16_swap_b32_e32 v48, v49
	s_waitcnt lgkmcnt(0)
	v_add_f32_e32 v48, v48, v49
	v_xor_b32_e32 v49, 32, v191
	v_cmp_lt_i32_e32 vcc, v49, v50
	s_nop 1
	v_cndmask_b32_e32 v49, v191, v49, vcc
	v_lshlrev_b32_e32 v49, 2, v49
	v_mov_b32_e32 v49, v48
	s_nop 1
	v_permlane32_swap_b32_e32 v48, v49
	s_and_saveexec_b64 s[70:71], s[4:5]
	s_cbranch_execz .LBB0_659
	s_andn2_b64 vcc, exec, s[64:65]
	s_waitcnt lgkmcnt(0)
	v_add_f32_e32 v48, v48, v49
	s_cbranch_vccnz .LBB0_712
	v_lshlrev_b64 v[50:51], 5, v[166:167]
	v_lshl_add_u64 v[50:51], s[40:41], 0, v[50:51]
	v_lshl_add_u64 v[50:51], s[66:67], 2, v[50:51]
	s_lshl_b32 s72, s92, 2
	s_mov_b32 s73, s17
	v_lshl_add_u64 v[50:51], v[50:51], 0, s[72:73]
	global_store_dword v[50:51], v48, off
	s_cbranch_execnz .LBB0_659

.LBB0_670:
	s_andn2_b64 vcc, exec, s[70:71]
	s_cbranch_vccnz .LBB0_676
	s_waitcnt lgkmcnt(1)
	v_mul_f32_e32 v32, v29, v29
	v_mul_f32_e32 v33, v31, v31
	v_fmac_f32_e32 v32, v28, v28
	v_fmac_f32_e32 v33, v30, v30
	v_add_f32_e32 v32, v32, v33
	v_mul_f32_e32 v33, v25, v25
	v_mul_f32_e32 v34, v27, v27
	v_fmac_f32_e32 v33, v24, v24
	v_fmac_f32_e32 v34, v26, v26
	v_add_f32_e32 v33, v33, v34
	v_add_f32_e32 v32, v32, v33
	v_mul_f32_e32 v33, v21, v21
	v_mul_f32_e32 v34, v23, v23
	v_fmac_f32_e32 v33, v20, v20
	v_fmac_f32_e32 v34, v22, v22
	v_add_f32_e32 v33, v33, v34
	v_mul_f32_e32 v34, v17, v17
	v_mul_f32_e32 v35, v19, v19
	v_fmac_f32_e32 v34, v16, v16
	v_fmac_f32_e32 v35, v18, v18
	v_add_f32_e32 v34, v34, v35
	v_add_f32_e32 v33, v33, v34
	v_and_b32_e32 v34, 64, v191
	v_add_f32_e32 v32, v32, v33
	v_xor_b32_e32 v33, 16, v191
	v_add_u32_e32 v34, 64, v34
	v_cmp_lt_i32_e32 vcc, v33, v34
	s_nop 1
	v_cndmask_b32_e32 v33, v191, v33, vcc
	v_lshlrev_b32_e32 v33, 2, v33
	v_mov_b32_e32 v33, v32
	s_nop 1
	v_permlane16_swap_b32_e32 v32, v33
	s_waitcnt lgkmcnt(0)
	v_add_f32_e32 v32, v32, v33
	v_xor_b32_e32 v33, 32, v191
	v_cmp_lt_i32_e32 vcc, v33, v34
	s_nop 1
	v_cndmask_b32_e32 v33, v191, v33, vcc
	v_lshlrev_b32_e32 v33, 2, v33
	v_mov_b32_e32 v33, v32
	s_nop 1
	v_permlane32_swap_b32_e32 v32, v33
	s_and_saveexec_b64 s[70:71], s[4:5]
	s_cbranch_execz .LBB0_675
	s_andn2_b64 vcc, exec, s[64:65]
	s_waitcnt lgkmcnt(0)
	v_add_f32_e32 v32, v32, v33
	s_cbranch_vccnz .LBB0_713
	v_lshlrev_b64 v[34:35], 5, v[162:163]
	v_lshl_add_u64 v[34:35], s[40:41], 0, v[34:35]
	v_lshl_add_u64 v[34:35], s[66:67], 2, v[34:35]
	s_lshl_b32 s72, s92, 2
	s_mov_b32 s73, s17
	v_lshl_add_u64 v[34:35], v[34:35], 0, s[72:73]
	global_store_dword v[34:35], v32, off
	s_cbranch_execnz .LBB0_675

.LBB0_686:
	s_andn2_b64 vcc, exec, s[10:11]
	s_cbranch_vccnz .LBB0_692
	s_waitcnt lgkmcnt(1)
	v_mul_f32_e32 v16, v13, v13
	v_mul_f32_e32 v17, v15, v15
	v_fmac_f32_e32 v16, v12, v12
	v_fmac_f32_e32 v17, v14, v14
	v_add_f32_e32 v16, v16, v17
	v_mul_f32_e32 v17, v9, v9
	v_mul_f32_e32 v18, v11, v11
	v_fmac_f32_e32 v17, v8, v8
	v_fmac_f32_e32 v18, v10, v10
	v_add_f32_e32 v17, v17, v18
	v_add_f32_e32 v16, v16, v17
	v_mul_f32_e32 v17, v5, v5
	v_mul_f32_e32 v18, v7, v7
	v_fmac_f32_e32 v17, v4, v4
	v_fmac_f32_e32 v18, v6, v6
	v_add_f32_e32 v17, v17, v18
	v_mul_f32_e32 v18, v1, v1
	v_mul_f32_e32 v19, v3, v3
	v_fmac_f32_e32 v18, v0, v0
	v_fmac_f32_e32 v19, v2, v2
	v_add_f32_e32 v18, v18, v19
	v_add_f32_e32 v17, v17, v18
	v_and_b32_e32 v18, 64, v191
	v_add_f32_e32 v16, v16, v17
	v_xor_b32_e32 v17, 16, v191
	v_add_u32_e32 v18, 64, v18
	v_cmp_lt_i32_e32 vcc, v17, v18
	s_nop 1
	v_cndmask_b32_e32 v17, v191, v17, vcc
	v_lshlrev_b32_e32 v17, 2, v17
	v_mov_b32_e32 v17, v16
	s_nop 1
	v_permlane16_swap_b32_e32 v16, v17
	s_waitcnt lgkmcnt(0)
	v_add_f32_e32 v16, v16, v17
	v_xor_b32_e32 v17, 32, v191
	v_cmp_lt_i32_e32 vcc, v17, v18
	s_nop 1
	v_cndmask_b32_e32 v17, v191, v17, vcc
	v_lshlrev_b32_e32 v17, 2, v17
	v_mov_b32_e32 v17, v16
	s_nop 1
	v_permlane32_swap_b32_e32 v16, v17
	s_and_saveexec_b64 s[8:9], s[4:5]
	s_cbranch_execz .LBB0_691
	s_andn2_b64 vcc, exec, s[64:65]
	s_waitcnt lgkmcnt(0)
	v_add_f32_e32 v16, v16, v17
	s_cbranch_vccnz .LBB0_714
	v_lshlrev_b64 v[18:19], 5, v[160:161]
	v_lshl_add_u64 v[18:19], s[40:41], 0, v[18:19]
	v_lshl_add_u64 v[18:19], s[66:67], 2, v[18:19]
	s_lshl_b32 s10, s92, 2
	s_mov_b32 s11, s17
	v_lshl_add_u64 v[18:19], v[18:19], 0, s[10:11]
	global_store_dword v[18:19], v16, off
	s_cbranch_execnz .LBB0_691

.LBB0_941:
	v_mbcnt_lo_u32_b32 v184, -1, 0
	v_mbcnt_hi_u32_b32 v184, -1, v184
	s_lshl_b32 s9, s34, 8
	v_ashrrev_i32_e32 v183, 3, v184
	v_add_u32_e32 v182, s60, v183
	v_add_u32_e32 v128, s9, v182
	v_ashrrev_i32_e32 v129, 31, v128
	s_lshl_b32 s36, s8, 8
	v_lshlrev_b64 v[128:129], 10, v[128:129]
	s_ashr_i32 s37, s36, 31
	v_lshl_add_u64 v[168:169], v[128:129], 0, s[36:37]
	v_or_b32_e32 v168, s66, v168
	v_lshlrev_b32_e32 v128, 4, v184
	v_and_b32_e32 v156, 0x70, v128
	v_lshl_add_u64 v[128:129], v[168:169], 1, s[12:13]
	v_lshl_add_u64 v[170:171], v[128:129], 0, v[156:157]
	v_add_co_u32_e32 v128, vcc, s55, v170
	v_mul_lo_u32 v183, v183, s71
	s_nop 0
	v_addc_co_u32_e32 v129, vcc, 0, v171, vcc
	global_load_dwordx4 v[186:189], v[170:171], off nt
	global_load_dwordx4 v[190:193], v[128:129], off nt
	v_add_co_u32_e32 v128, vcc, s64, v170
	v_add_u32_e32 v183, s70, v183
	s_nop 0
	v_addc_co_u32_e32 v129, vcc, 0, v171, vcc
	v_add_co_u32_e32 v130, vcc, s74, v170
	v_add_u32_e32 v183, v183, v156
	s_nop 0
	v_addc_co_u32_e32 v131, vcc, 0, v171, vcc
	v_add_co_u32_e32 v132, vcc, s53, v170
	v_add_u32_e32 v185, v174, v172
	s_nop 0
	v_addc_co_u32_e32 v133, vcc, 0, v171, vcc
	v_add_co_u32_e32 v134, vcc, s54, v170
	s_nop 1
	v_addc_co_u32_e32 v135, vcc, 0, v171, vcc
	v_add_co_u32_e32 v194, vcc, s63, v170
	s_nop 1
	v_addc_co_u32_e32 v195, vcc, 0, v171, vcc
	v_add_co_u32_e32 v196, vcc, s65, v170
	s_nop 1
	v_addc_co_u32_e32 v197, vcc, 0, v171, vcc
	global_load_dwordx4 v[144:147], v[128:129], off nt
	global_load_dwordx4 v[148:151], v[130:131], off nt
	global_load_dwordx4 v[136:139], v[132:133], off nt
	global_load_dwordx4 v[140:143], v[134:135], off nt
	s_nop 0
	global_load_dwordx4 v[128:131], v[194:195], off nt
	global_load_dwordx4 v[132:135], v[196:197], off nt
	s_waitcnt vmcnt(0)
	ds_write_b128 v183, v[186:189]
	ds_write_b128 v183, v[190:193] offset:1152
	ds_read_b128 v[186:189], v185
	ds_read_b128 v[190:193], v185 offset:64
	s_waitcnt lgkmcnt(1)
	v_lshlrev_b32_e32 v194, 16, v186
	v_and_b32_e32 v195, 0xffff0000, v186
	v_lshlrev_b32_e32 v186, 16, v187
	v_and_b32_e32 v187, 0xffff0000, v187
	v_lshlrev_b32_e32 v196, 16, v188
	v_and_b32_e32 v197, 0xffff0000, v188
	v_lshlrev_b32_e32 v188, 16, v189
	v_and_b32_e32 v189, 0xffff0000, v189
	s_waitcnt lgkmcnt(0)
	v_lshlrev_b32_e32 v198, 16, v190
	v_and_b32_e32 v199, 0xffff0000, v190
	v_lshlrev_b32_e32 v190, 16, v191
	v_and_b32_e32 v191, 0xffff0000, v191
	v_lshlrev_b32_e32 v200, 16, v192
	v_and_b32_e32 v201, 0xffff0000, v192
	v_lshlrev_b32_e32 v192, 16, v193
	v_and_b32_e32 v193, 0xffff0000, v193
	v_pk_add_f32 v[124:125], v[124:125], v[194:195]
	v_pk_add_f32 v[126:127], v[126:127], v[186:187]
	v_pk_add_f32 v[120:121], v[120:121], v[196:197]
	v_pk_add_f32 v[122:123], v[122:123], v[188:189]
	v_pk_add_f32 v[108:109], v[108:109], v[198:199]
	v_pk_add_f32 v[110:111], v[110:111], v[190:191]
	v_pk_add_f32 v[100:101], v[100:101], v[200:201]
	v_pk_add_f32 v[102:103], v[102:103], v[192:193]
	v_pk_mul_f32 v[186:187], v[124:125], v[124:125]
	v_pk_mul_f32 v[188:189], v[126:127], v[126:127]
	v_pk_mul_f32 v[190:191], v[120:121], v[120:121]
	v_pk_mul_f32 v[192:193], v[122:123], v[122:123]
	v_pk_mul_f32 v[194:195], v[108:109], v[108:109]
	v_pk_mul_f32 v[196:197], v[110:111], v[110:111]
	v_pk_mul_f32 v[198:199], v[100:101], v[100:101]
	v_pk_mul_f32 v[200:201], v[102:103], v[102:103]
	v_add_f32_e32 v198, v198, v199
	v_add_f32_e32 v156, v200, v201
	v_add_f32_e32 v196, v196, v197
	v_add_f32_e32 v194, v194, v195
	v_add_f32_e32 v192, v192, v193
	v_add_f32_e32 v190, v190, v191
	v_add_f32_e32 v188, v188, v189
	v_add_f32_e32 v186, v186, v187
	v_add_f32_e32 v156, v198, v156
	v_add_f32_e32 v187, v194, v196
	v_add_f32_e32 v189, v190, v192
	v_add_f32_e32 v186, v186, v188
	v_add_f32_e32 v156, v187, v156
	v_add_f32_e32 v186, v186, v189
	v_and_b32_e32 v187, 64, v178
	v_add_f32_e32 v186, v186, v156
	v_xor_b32_e32 v156, 16, v178
	v_add_u32_e32 v188, 64, v187
	v_cmp_lt_i32_e32 vcc, v156, v188
	s_nop 1
	v_cndmask_b32_e32 v156, v178, v156, vcc
	v_lshlrev_b32_e32 v156, 2, v156
	v_mov_b32_e32 v187, v186
	s_nop 1
	v_permlane16_swap_b32_e32 v186, v187
	s_waitcnt lgkmcnt(0)
	v_add_f32_e32 v187, v186, v187
	v_xor_b32_e32 v186, 32, v178
	v_cmp_lt_i32_e32 vcc, v186, v188
	s_nop 1
	v_cndmask_b32_e32 v186, v178, v186, vcc
	v_lshlrev_b32_e32 v186, 2, v186
	v_mov_b32_e32 v188, v187
	s_nop 1
	v_permlane32_swap_b32_e32 v187, v188
	s_and_saveexec_b64 s[6:7], s[0:1]
	s_cbranch_execz .LBB0_943
	s_waitcnt lgkmcnt(0)
	v_add_f32_e32 v187, v187, v188
	ds_write_b32 v180, v187
.LBB0_943:
	s_or_b64 exec, exec, s[6:7]
	ds_write_b128 v183, v[144:147]
	ds_write_b128 v183, v[148:151] offset:1152
	ds_read_b128 v[144:147], v185
	ds_read_b128 v[148:151], v185 offset:64
	s_waitcnt lgkmcnt(1)
	v_lshlrev_b32_e32 v188, 16, v144
	v_and_b32_e32 v189, 0xffff0000, v144
	v_lshlrev_b32_e32 v144, 16, v145
	v_and_b32_e32 v145, 0xffff0000, v145
	v_pk_add_f32 v[114:115], v[114:115], v[144:145]
	v_lshlrev_b32_e32 v144, 16, v146
	v_and_b32_e32 v145, 0xffff0000, v146
	v_pk_add_f32 v[116:117], v[116:117], v[144:145]
	v_lshlrev_b32_e32 v144, 16, v147
	v_and_b32_e32 v145, 0xffff0000, v147
	v_pk_add_f32 v[118:119], v[118:119], v[144:145]
	s_waitcnt lgkmcnt(0)
	v_lshlrev_b32_e32 v144, 16, v148
	v_and_b32_e32 v145, 0xffff0000, v148
	v_pk_add_f32 v[88:89], v[88:89], v[144:145]
	v_lshlrev_b32_e32 v144, 16, v149
	v_and_b32_e32 v145, 0xffff0000, v149
	v_pk_add_f32 v[90:91], v[90:91], v[144:145]
	v_lshlrev_b32_e32 v144, 16, v150
	v_and_b32_e32 v145, 0xffff0000, v150
	v_pk_add_f32 v[92:93], v[92:93], v[144:145]
	v_lshlrev_b32_e32 v144, 16, v151
	v_and_b32_e32 v145, 0xffff0000, v151
	v_pk_add_f32 v[112:113], v[112:113], v[188:189]
	v_pk_add_f32 v[94:95], v[94:95], v[144:145]
	v_pk_mul_f32 v[144:145], v[112:113], v[112:113]
	v_pk_mul_f32 v[146:147], v[114:115], v[114:115]
	v_pk_mul_f32 v[148:149], v[116:117], v[116:117]
	v_pk_mul_f32 v[150:151], v[118:119], v[118:119]
	v_pk_mul_f32 v[188:189], v[88:89], v[88:89]
	v_pk_mul_f32 v[190:191], v[90:91], v[90:91]
	v_pk_mul_f32 v[192:193], v[92:93], v[92:93]
	v_pk_mul_f32 v[194:195], v[94:95], v[94:95]
	v_add_f32_e32 v192, v192, v193
	v_add_f32_e32 v187, v194, v195
	v_add_f32_e32 v190, v190, v191
	v_add_f32_e32 v188, v188, v189
	v_add_f32_e32 v150, v150, v151
	v_add_f32_e32 v148, v148, v149
	v_add_f32_e32 v146, v146, v147
	v_add_f32_e32 v144, v144, v145
	v_add_f32_e32 v187, v192, v187
	v_add_f32_e32 v188, v188, v190
	v_add_f32_e32 v148, v148, v150
	v_add_f32_e32 v144, v144, v146
	v_add_f32_e32 v187, v188, v187
	v_add_f32_e32 v144, v144, v148
	v_add_f32_e32 v144, v144, v187
	v_mov_b32_e32 v145, v144
	s_nop 1
	v_permlane16_swap_b32_e32 v144, v145
	s_waitcnt lgkmcnt(0)
	v_add_f32_e32 v144, v144, v145
	v_mov_b32_e32 v145, v144
	s_nop 1
	v_permlane32_swap_b32_e32 v144, v145
	s_and_saveexec_b64 s[6:7], s[0:1]
	s_cbranch_execz .LBB0_945
	s_waitcnt lgkmcnt(0)
	v_add_f32_e32 v144, v144, v145
	ds_write_b32 v180, v144 offset:256
.LBB0_945:
	s_or_b64 exec, exec, s[6:7]
	ds_write_b128 v183, v[136:139]
	ds_write_b128 v183, v[140:143] offset:1152
	ds_read_b128 v[136:139], v185
	ds_read_b128 v[140:143], v185 offset:64
	s_waitcnt lgkmcnt(1)
	v_lshlrev_b32_e32 v144, 16, v136
	v_and_b32_e32 v145, 0xffff0000, v136
	v_lshlrev_b32_e32 v136, 16, v137
	v_and_b32_e32 v137, 0xffff0000, v137
	v_pk_add_f32 v[98:99], v[98:99], v[136:137]
	v_lshlrev_b32_e32 v136, 16, v138
	v_and_b32_e32 v137, 0xffff0000, v138
	v_pk_add_f32 v[104:105], v[104:105], v[136:137]
	v_lshlrev_b32_e32 v136, 16, v139
	v_and_b32_e32 v137, 0xffff0000, v139
	v_pk_add_f32 v[106:107], v[106:107], v[136:137]
	s_waitcnt lgkmcnt(0)
	v_lshlrev_b32_e32 v136, 16, v140
	v_and_b32_e32 v137, 0xffff0000, v140
	v_pk_add_f32 v[84:85], v[84:85], v[136:137]
	v_lshlrev_b32_e32 v136, 16, v141
	v_and_b32_e32 v137, 0xffff0000, v141
	v_pk_add_f32 v[86:87], v[86:87], v[136:137]
	v_lshlrev_b32_e32 v136, 16, v142
	v_and_b32_e32 v137, 0xffff0000, v142
	v_pk_add_f32 v[80:81], v[80:81], v[136:137]
	v_lshlrev_b32_e32 v136, 16, v143
	v_and_b32_e32 v137, 0xffff0000, v143
	v_pk_add_f32 v[96:97], v[96:97], v[144:145]
	v_pk_add_f32 v[82:83], v[82:83], v[136:137]
	v_pk_mul_f32 v[136:137], v[96:97], v[96:97]
	v_pk_mul_f32 v[138:139], v[98:99], v[98:99]
	v_pk_mul_f32 v[140:141], v[104:105], v[104:105]
	v_pk_mul_f32 v[142:143], v[106:107], v[106:107]
	v_pk_mul_f32 v[144:145], v[84:85], v[84:85]
	v_pk_mul_f32 v[146:147], v[86:87], v[86:87]
	v_pk_mul_f32 v[148:149], v[80:81], v[80:81]
	v_pk_mul_f32 v[150:151], v[82:83], v[82:83]
	v_add_f32_e32 v148, v148, v149
	v_add_f32_e32 v150, v150, v151
	v_add_f32_e32 v146, v146, v147
	v_add_f32_e32 v144, v144, v145
	v_add_f32_e32 v142, v142, v143
	v_add_f32_e32 v140, v140, v141
	v_add_f32_e32 v138, v138, v139
	v_add_f32_e32 v136, v136, v137
	v_add_f32_e32 v148, v148, v150
	v_add_f32_e32 v144, v144, v146
	v_add_f32_e32 v140, v140, v142
	v_add_f32_e32 v136, v136, v138
	v_add_f32_e32 v144, v144, v148
	v_add_f32_e32 v136, v136, v140
	v_add_f32_e32 v136, v136, v144
	v_mov_b32_e32 v137, v136
	s_nop 1
	v_permlane16_swap_b32_e32 v136, v137
	s_waitcnt lgkmcnt(0)
	v_add_f32_e32 v136, v136, v137
	v_mov_b32_e32 v137, v136
	s_nop 1
	v_permlane32_swap_b32_e32 v136, v137
	s_and_saveexec_b64 s[6:7], s[0:1]
	s_cbranch_execz .LBB0_947
	s_waitcnt lgkmcnt(0)
	v_add_f32_e32 v136, v136, v137
	ds_write_b32 v180, v136 offset:512
.LBB0_947:
	s_or_b64 exec, exec, s[6:7]
	ds_write_b128 v183, v[128:131]
	ds_write_b128 v183, v[132:135] offset:1152
	ds_read_b128 v[128:131], v185
	ds_read_b128 v[132:135], v185 offset:64
	s_waitcnt lgkmcnt(1)
	v_lshlrev_b32_e32 v136, 16, v128
	v_and_b32_e32 v137, 0xffff0000, v128
	v_lshlrev_b32_e32 v128, 16, v129
	v_and_b32_e32 v129, 0xffff0000, v129
	v_pk_add_f32 v[78:79], v[78:79], v[128:129]
	v_lshlrev_b32_e32 v128, 16, v130
	v_and_b32_e32 v129, 0xffff0000, v130
	v_pk_add_f32 v[72:73], v[72:73], v[128:129]
	v_lshlrev_b32_e32 v128, 16, v131
	v_and_b32_e32 v129, 0xffff0000, v131
	v_pk_add_f32 v[74:75], v[74:75], v[128:129]
	s_waitcnt lgkmcnt(0)
	v_lshlrev_b32_e32 v128, 16, v132
	v_and_b32_e32 v129, 0xffff0000, v132
	v_pk_add_f32 v[68:69], v[68:69], v[128:129]
	v_lshlrev_b32_e32 v128, 16, v133
	v_and_b32_e32 v129, 0xffff0000, v133
	v_pk_add_f32 v[70:71], v[70:71], v[128:129]
	v_lshlrev_b32_e32 v128, 16, v134
	v_and_b32_e32 v129, 0xffff0000, v134
	v_pk_add_f32 v[64:65], v[64:65], v[128:129]
	v_lshlrev_b32_e32 v128, 16, v135
	v_and_b32_e32 v129, 0xffff0000, v135
	v_pk_add_f32 v[76:77], v[76:77], v[136:137]
	v_pk_add_f32 v[66:67], v[66:67], v[128:129]
	v_pk_mul_f32 v[128:129], v[76:77], v[76:77]
	v_pk_mul_f32 v[130:131], v[78:79], v[78:79]
	v_pk_mul_f32 v[132:133], v[72:73], v[72:73]
	v_pk_mul_f32 v[134:135], v[74:75], v[74:75]
	v_pk_mul_f32 v[136:137], v[68:69], v[68:69]
	v_pk_mul_f32 v[138:139], v[70:71], v[70:71]
	v_pk_mul_f32 v[140:141], v[64:65], v[64:65]
	v_pk_mul_f32 v[142:143], v[66:67], v[66:67]
	v_add_f32_e32 v140, v140, v141
	v_add_f32_e32 v142, v142, v143
	v_add_f32_e32 v138, v138, v139
	v_add_f32_e32 v136, v136, v137
	v_add_f32_e32 v134, v134, v135
	v_add_f32_e32 v132, v132, v133
	v_add_f32_e32 v130, v130, v131
	v_add_f32_e32 v128, v128, v129
	v_add_f32_e32 v140, v140, v142
	v_add_f32_e32 v136, v136, v138
	v_add_f32_e32 v132, v132, v134
	v_add_f32_e32 v128, v128, v130
	v_add_f32_e32 v136, v136, v140
	v_add_f32_e32 v128, v128, v132
	v_add_f32_e32 v128, v128, v136
	v_mov_b32_e32 v129, v128
	s_nop 1
	v_permlane16_swap_b32_e32 v128, v129
	s_waitcnt lgkmcnt(0)
	v_add_f32_e32 v128, v128, v129
	v_mov_b32_e32 v129, v128
	s_nop 1
	v_permlane32_swap_b32_e32 v128, v129
	s_and_saveexec_b64 s[6:7], s[0:1]
	s_cbranch_execz .LBB0_949
	s_waitcnt lgkmcnt(0)
	v_add_f32_e32 v128, v128, v129
	ds_write_b32 v180, v128 offset:768
.LBB0_949:
	s_or_b64 exec, exec, s[6:7]
	v_add_co_u32_e32 v128, vcc, 0x40000, v170
	s_waitcnt lgkmcnt(0)
	s_nop 0
	v_addc_co_u32_e32 v129, vcc, 0, v171, vcc
	v_add_co_u32_e32 v130, vcc, 0x44000, v170
	s_nop 1
	v_addc_co_u32_e32 v131, vcc, 0, v171, vcc
	global_load_dwordx4 v[188:191], v[128:129], off nt
	global_load_dwordx4 v[192:195], v[130:131], off nt
	v_add_co_u32_e32 v128, vcc, 0x48000, v170
	s_nop 1
	v_addc_co_u32_e32 v129, vcc, 0, v171, vcc
	v_add_co_u32_e32 v130, vcc, 0x4c000, v170
	s_nop 1
	v_addc_co_u32_e32 v131, vcc, 0, v171, vcc
	v_add_co_u32_e32 v132, vcc, 0x50000, v170
	global_load_dwordx4 v[144:147], v[128:129], off nt
	global_load_dwordx4 v[148:151], v[130:131], off nt
	v_addc_co_u32_e32 v133, vcc, 0, v171, vcc
	v_add_co_u32_e32 v128, vcc, 0x54000, v170
	s_nop 1
	v_addc_co_u32_e32 v129, vcc, 0, v171, vcc
	v_add_co_u32_e32 v130, vcc, 0x58000, v170
	global_load_dwordx4 v[136:139], v[132:133], off nt
	global_load_dwordx4 v[140:143], v[128:129], off nt
	v_addc_co_u32_e32 v131, vcc, 0, v171, vcc
	v_add_co_u32_e32 v132, vcc, 0x5c000, v170
	s_nop 1
	v_addc_co_u32_e32 v133, vcc, 0, v171, vcc
	global_load_dwordx4 v[128:131], v[130:131], off nt
	s_nop 0
	global_load_dwordx4 v[132:135], v[132:133], off nt
	s_waitcnt vmcnt(7)
	ds_write_b128 v183, v[188:191]
	s_waitcnt vmcnt(6)
	ds_write_b128 v183, v[192:195] offset:1152
	ds_read_b128 v[188:191], v185
	ds_read_b128 v[192:195], v185 offset:64
	s_waitcnt lgkmcnt(1)
	v_lshlrev_b32_e32 v170, 16, v188
	v_and_b32_e32 v171, 0xffff0000, v188
	v_lshlrev_b32_e32 v188, 16, v189
	v_and_b32_e32 v189, 0xffff0000, v189
	v_lshlrev_b32_e32 v196, 16, v190
	v_and_b32_e32 v197, 0xffff0000, v190
	v_lshlrev_b32_e32 v190, 16, v191
	v_and_b32_e32 v191, 0xffff0000, v191
	s_waitcnt lgkmcnt(0)
	v_lshlrev_b32_e32 v198, 16, v192
	v_and_b32_e32 v199, 0xffff0000, v192
	v_lshlrev_b32_e32 v192, 16, v193
	v_and_b32_e32 v193, 0xffff0000, v193
	v_lshlrev_b32_e32 v200, 16, v194
	v_and_b32_e32 v201, 0xffff0000, v194
	v_lshlrev_b32_e32 v194, 16, v195
	v_and_b32_e32 v195, 0xffff0000, v195
	v_pk_add_f32 v[60:61], v[60:61], v[170:171]
	v_pk_add_f32 v[62:63], v[62:63], v[188:189]
	v_pk_add_f32 v[56:57], v[56:57], v[196:197]
	v_pk_add_f32 v[58:59], v[58:59], v[190:191]
	v_pk_add_f32 v[52:53], v[52:53], v[198:199]
	v_pk_add_f32 v[54:55], v[54:55], v[192:193]
	v_pk_add_f32 v[48:49], v[48:49], v[200:201]
	v_pk_add_f32 v[50:51], v[50:51], v[194:195]
	v_pk_mul_f32 v[170:171], v[60:61], v[60:61]
	v_pk_mul_f32 v[188:189], v[62:63], v[62:63]
	v_pk_mul_f32 v[190:191], v[56:57], v[56:57]
	v_pk_mul_f32 v[192:193], v[58:59], v[58:59]
	v_pk_mul_f32 v[194:195], v[52:53], v[52:53]
	v_pk_mul_f32 v[196:197], v[54:55], v[54:55]
	v_pk_mul_f32 v[198:199], v[48:49], v[48:49]
	v_pk_mul_f32 v[200:201], v[50:51], v[50:51]
	v_add_f32_e32 v198, v198, v199
	v_add_f32_e32 v187, v200, v201
	v_add_f32_e32 v196, v196, v197
	v_add_f32_e32 v194, v194, v195
	v_add_f32_e32 v192, v192, v193
	v_add_f32_e32 v190, v190, v191
	v_add_f32_e32 v188, v188, v189
	v_add_f32_e32 v170, v170, v171
	v_add_f32_e32 v187, v198, v187
	v_add_f32_e32 v191, v194, v196
	v_add_f32_e32 v190, v190, v192
	v_add_f32_e32 v170, v170, v188
	v_add_f32_e32 v187, v191, v187
	v_add_f32_e32 v170, v170, v190
	v_add_f32_e32 v170, v170, v187
	v_mov_b32_e32 v171, v170
	s_nop 1
	v_permlane16_swap_b32_e32 v170, v171
	s_waitcnt lgkmcnt(0)
	v_add_f32_e32 v170, v170, v171
	v_mov_b32_e32 v171, v170
	s_nop 1
	v_permlane32_swap_b32_e32 v170, v171
	s_and_saveexec_b64 s[6:7], s[0:1]
	s_cbranch_execz .LBB0_951
	s_waitcnt lgkmcnt(0)
	v_add_f32_e32 v170, v170, v171
	ds_write_b32 v180, v170 offset:2048
.LBB0_951:
	s_or_b64 exec, exec, s[6:7]
	s_waitcnt vmcnt(5)
	ds_write_b128 v183, v[144:147]
	s_waitcnt vmcnt(4)
	ds_write_b128 v183, v[148:151] offset:1152
	ds_read_b128 v[144:147], v185
	ds_read_b128 v[148:151], v185 offset:64
	s_waitcnt lgkmcnt(1)
	v_lshlrev_b32_e32 v170, 16, v144
	v_and_b32_e32 v171, 0xffff0000, v144
	v_lshlrev_b32_e32 v144, 16, v145
	v_and_b32_e32 v145, 0xffff0000, v145
	v_pk_add_f32 v[46:47], v[46:47], v[144:145]
	v_lshlrev_b32_e32 v144, 16, v146
	v_and_b32_e32 v145, 0xffff0000, v146
	v_pk_add_f32 v[40:41], v[40:41], v[144:145]
	v_lshlrev_b32_e32 v144, 16, v147
	v_and_b32_e32 v145, 0xffff0000, v147
	v_pk_add_f32 v[42:43], v[42:43], v[144:145]
	s_waitcnt lgkmcnt(0)
	v_lshlrev_b32_e32 v144, 16, v148
	v_and_b32_e32 v145, 0xffff0000, v148
	v_pk_add_f32 v[36:37], v[36:37], v[144:145]
	v_lshlrev_b32_e32 v144, 16, v149
	v_and_b32_e32 v145, 0xffff0000, v149
	v_pk_add_f32 v[38:39], v[38:39], v[144:145]
	v_lshlrev_b32_e32 v144, 16, v150
	v_and_b32_e32 v145, 0xffff0000, v150
	v_pk_add_f32 v[32:33], v[32:33], v[144:145]
	v_lshlrev_b32_e32 v144, 16, v151
	v_and_b32_e32 v145, 0xffff0000, v151
	v_pk_add_f32 v[44:45], v[44:45], v[170:171]
	v_pk_add_f32 v[34:35], v[34:35], v[144:145]
	v_pk_mul_f32 v[144:145], v[44:45], v[44:45]
	v_pk_mul_f32 v[146:147], v[46:47], v[46:47]
	v_pk_mul_f32 v[148:149], v[40:41], v[40:41]
	v_pk_mul_f32 v[150:151], v[42:43], v[42:43]
	v_pk_mul_f32 v[170:171], v[36:37], v[36:37]
	v_pk_mul_f32 v[188:189], v[38:39], v[38:39]
	v_pk_mul_f32 v[190:191], v[32:33], v[32:33]
	v_pk_mul_f32 v[192:193], v[34:35], v[34:35]
	v_add_f32_e32 v190, v190, v191
	v_add_f32_e32 v187, v192, v193
	v_add_f32_e32 v188, v188, v189
	v_add_f32_e32 v170, v170, v171
	v_add_f32_e32 v150, v150, v151
	v_add_f32_e32 v148, v148, v149
	v_add_f32_e32 v146, v146, v147
	v_add_f32_e32 v144, v144, v145
	v_add_f32_e32 v187, v190, v187
	v_add_f32_e32 v170, v170, v188
	v_add_f32_e32 v148, v148, v150
	v_add_f32_e32 v144, v144, v146
	v_add_f32_e32 v170, v170, v187
	v_add_f32_e32 v144, v144, v148
	v_add_f32_e32 v144, v144, v170
	v_mov_b32_e32 v145, v144
	s_nop 1
	v_permlane16_swap_b32_e32 v144, v145
	s_waitcnt lgkmcnt(0)
	v_add_f32_e32 v144, v144, v145
	v_mov_b32_e32 v145, v144
	s_nop 1
	v_permlane32_swap_b32_e32 v144, v145
	s_and_saveexec_b64 s[6:7], s[0:1]
	s_cbranch_execz .LBB0_953
	s_waitcnt lgkmcnt(0)
	v_add_f32_e32 v144, v144, v145
	ds_write_b32 v180, v144 offset:2304
.LBB0_953:
	s_or_b64 exec, exec, s[6:7]
	s_waitcnt vmcnt(3)
	ds_write_b128 v183, v[136:139]
	s_waitcnt vmcnt(2)
	ds_write_b128 v183, v[140:143] offset:1152
	ds_read_b128 v[136:139], v185
	ds_read_b128 v[140:143], v185 offset:64
	s_waitcnt lgkmcnt(1)
	v_lshlrev_b32_e32 v144, 16, v136
	v_and_b32_e32 v145, 0xffff0000, v136
	v_lshlrev_b32_e32 v136, 16, v137
	v_and_b32_e32 v137, 0xffff0000, v137
	v_pk_add_f32 v[30:31], v[30:31], v[136:137]
	v_lshlrev_b32_e32 v136, 16, v138
	v_and_b32_e32 v137, 0xffff0000, v138
	v_pk_add_f32 v[24:25], v[24:25], v[136:137]
	v_lshlrev_b32_e32 v136, 16, v139
	v_and_b32_e32 v137, 0xffff0000, v139
	v_pk_add_f32 v[26:27], v[26:27], v[136:137]
	s_waitcnt lgkmcnt(0)
	v_lshlrev_b32_e32 v136, 16, v140
	v_and_b32_e32 v137, 0xffff0000, v140
	v_pk_add_f32 v[20:21], v[20:21], v[136:137]
	v_lshlrev_b32_e32 v136, 16, v141
	v_and_b32_e32 v137, 0xffff0000, v141
	v_pk_add_f32 v[22:23], v[22:23], v[136:137]
	v_lshlrev_b32_e32 v136, 16, v142
	v_and_b32_e32 v137, 0xffff0000, v142
	v_pk_add_f32 v[16:17], v[16:17], v[136:137]
	v_lshlrev_b32_e32 v136, 16, v143
	v_and_b32_e32 v137, 0xffff0000, v143
	v_pk_add_f32 v[28:29], v[28:29], v[144:145]
	v_pk_add_f32 v[18:19], v[18:19], v[136:137]
	v_pk_mul_f32 v[136:137], v[28:29], v[28:29]
	v_pk_mul_f32 v[138:139], v[30:31], v[30:31]
	v_pk_mul_f32 v[140:141], v[24:25], v[24:25]
	v_pk_mul_f32 v[142:143], v[26:27], v[26:27]
	v_pk_mul_f32 v[144:145], v[20:21], v[20:21]
	v_pk_mul_f32 v[146:147], v[22:23], v[22:23]
	v_pk_mul_f32 v[148:149], v[16:17], v[16:17]
	v_pk_mul_f32 v[150:151], v[18:19], v[18:19]
	v_add_f32_e32 v148, v148, v149
	v_add_f32_e32 v150, v150, v151
	v_add_f32_e32 v146, v146, v147
	v_add_f32_e32 v144, v144, v145
	v_add_f32_e32 v142, v142, v143
	v_add_f32_e32 v140, v140, v141
	v_add_f32_e32 v138, v138, v139
	v_add_f32_e32 v136, v136, v137
	v_add_f32_e32 v148, v148, v150
	v_add_f32_e32 v144, v144, v146
	v_add_f32_e32 v140, v140, v142
	v_add_f32_e32 v136, v136, v138
	v_add_f32_e32 v144, v144, v148
	v_add_f32_e32 v136, v136, v140
	v_add_f32_e32 v136, v136, v144
	v_mov_b32_e32 v137, v136
	s_nop 1
	v_permlane16_swap_b32_e32 v136, v137
	s_waitcnt lgkmcnt(0)
	v_add_f32_e32 v136, v136, v137
	v_mov_b32_e32 v137, v136
	s_nop 1
	v_permlane32_swap_b32_e32 v136, v137
	s_and_saveexec_b64 s[6:7], s[0:1]
	s_cbranch_execz .LBB0_955
	s_waitcnt lgkmcnt(0)
	v_add_f32_e32 v136, v136, v137
	ds_write_b32 v180, v136 offset:2560
.LBB0_955:
	s_or_b64 exec, exec, s[6:7]
	s_waitcnt vmcnt(1)
	ds_write_b128 v183, v[128:131]
	s_waitcnt vmcnt(0)
	ds_write_b128 v183, v[132:135] offset:1152
	ds_read_b128 v[128:131], v185
	ds_read_b128 v[132:135], v185 offset:64
	s_waitcnt lgkmcnt(1)
	v_lshlrev_b32_e32 v136, 16, v128
	v_and_b32_e32 v137, 0xffff0000, v128
	v_lshlrev_b32_e32 v128, 16, v129
	v_and_b32_e32 v129, 0xffff0000, v129
	v_pk_add_f32 v[14:15], v[14:15], v[128:129]
	v_lshlrev_b32_e32 v128, 16, v130
	v_and_b32_e32 v129, 0xffff0000, v130
	v_pk_add_f32 v[8:9], v[8:9], v[128:129]
	v_lshlrev_b32_e32 v128, 16, v131
	v_and_b32_e32 v129, 0xffff0000, v131
	v_pk_add_f32 v[10:11], v[10:11], v[128:129]
	s_waitcnt lgkmcnt(0)
	v_lshlrev_b32_e32 v128, 16, v132
	v_and_b32_e32 v129, 0xffff0000, v132
	v_pk_add_f32 v[4:5], v[4:5], v[128:129]
	v_lshlrev_b32_e32 v128, 16, v133
	v_and_b32_e32 v129, 0xffff0000, v133
	v_pk_add_f32 v[6:7], v[6:7], v[128:129]
	v_lshlrev_b32_e32 v128, 16, v134
	v_and_b32_e32 v129, 0xffff0000, v134
	v_pk_add_f32 v[0:1], v[0:1], v[128:129]
	v_lshlrev_b32_e32 v128, 16, v135
	v_and_b32_e32 v129, 0xffff0000, v135
	v_pk_add_f32 v[12:13], v[12:13], v[136:137]
	v_pk_add_f32 v[2:3], v[2:3], v[128:129]
	v_pk_mul_f32 v[128:129], v[12:13], v[12:13]
	v_pk_mul_f32 v[130:131], v[14:15], v[14:15]
	v_pk_mul_f32 v[132:133], v[8:9], v[8:9]
	v_pk_mul_f32 v[134:135], v[10:11], v[10:11]
	v_pk_mul_f32 v[136:137], v[4:5], v[4:5]
	v_pk_mul_f32 v[138:139], v[6:7], v[6:7]
	v_pk_mul_f32 v[140:141], v[0:1], v[0:1]
	v_pk_mul_f32 v[142:143], v[2:3], v[2:3]
	v_add_f32_e32 v140, v140, v141
	v_add_f32_e32 v142, v142, v143
	v_add_f32_e32 v138, v138, v139
	v_add_f32_e32 v136, v136, v137
	v_add_f32_e32 v134, v134, v135
	v_add_f32_e32 v132, v132, v133
	v_add_f32_e32 v130, v130, v131
	v_add_f32_e32 v128, v128, v129
	v_add_f32_e32 v140, v140, v142
	v_add_f32_e32 v136, v136, v138
	v_add_f32_e32 v132, v132, v134
	v_add_f32_e32 v128, v128, v130
	v_add_f32_e32 v136, v136, v140
	v_add_f32_e32 v128, v128, v132
	v_add_f32_e32 v128, v128, v136
	v_mov_b32_e32 v129, v128
	s_nop 1
	v_permlane16_swap_b32_e32 v128, v129
	s_waitcnt lgkmcnt(0)
	v_add_f32_e32 v128, v128, v129
	v_mov_b32_e32 v129, v128
	s_nop 1
	v_permlane32_swap_b32_e32 v128, v129
	s_and_saveexec_b64 s[6:7], s[0:1]
	s_cbranch_execz .LBB0_957
	s_waitcnt lgkmcnt(0)
	v_add_f32_e32 v128, v128, v129
	ds_write_b32 v180, v128 offset:2816
